# v70 with the saddr-form LDS-DMA conversion extended to 8 of the 9 K-loops (14 of 16 DMAs each) plus 64-bit accumulator clears
# baseline (speedup 1.0000x reference)
; #define PG8_STAGE(bufoff, gbase, voff) do { _Pragma("unroll") for (int _i = 0; _i < 2; ++_i) \
;         __builtin_amdgcn_global_load_lds((const unsigned*)((const char*)(gbase) + (voff)[_i]), (PG8_LAS unsigned*)(lds + (bufoff) + ldsw + _i * 8192), 16, 0, 0); } while (0)
; #define PG8_LDA(dst, b, h) do { _Pragma("unroll") for (int m = 0; m < 4; ++m) _Pragma("unroll") for (int k = 0; k < 2; ++k) dst[m][k] = *(const PG8_LAS bf16x8*)(lds + PG8_SA(b, h) + aoff + m * 2048 + k * 1024); } while (0)
; #define PG8_LDB(dst, b, h) do { _Pragma("unroll") for (int n = 0; n < 2; ++n) _Pragma("unroll") for (int k = 0; k < 2; ++k) dst[n][k] = *(const PG8_LAS bf16x8*)(lds + PG8_SB(b, h) + boff + n * 2048 + k * 1024); } while (0)
; #define PG8_MMA(ai, bj, At, Bt) do { __builtin_amdgcn_s_setprio(1); _Pragma("unroll") for (int m = 0; m < 4; ++m) _Pragma("unroll") for (int n = 0; n < 2; ++n) _Pragma("unroll") for (int k = 0; k < 2; ++k) \
;         acc[ai][bj][m][n] = __builtin_amdgcn_mfma_f32_16x16x32_bf16(Bt[n][k], At[m][k], acc[ai][bj][m][n], 0, 0, 0); __builtin_amdgcn_s_setprio(0); } while (0)
; #define PG8_WAIT_V(n) asm volatile("s_waitcnt vmcnt(" #n ")" ::: "memory")
; #define PG8_BAR __builtin_amdgcn_s_barrier()
; template <class Epi, class Sched, bool ALIGN_EPI = false, bool SP2 = false>
; __device__ __forceinline__ void gemm_phase(PG8_LAS unsigned char* lds, const Gemm g, const Sched& S, const Epi& E) {
;     ...
;         for (int t = 0; t < nt; t += 2) {
;             const bool last = (t == nt - 2);
;             const char* a1 = cA + (size_t)(t + 1) * kstep;
;             const char* a2 = last ? nA : cA + (size_t)(t + 2) * kstep; const char* b2 = last ? nB : cB + (size_t)(t + 2) * kstep;
;             const char* a3 = a2 + kstep; const char* b3 = b2 + kstep;
;             if (last && has_next) S.a_ready(nxt);
;             if constexpr (SP2) {
;             PG8_LDB(B0, 0, 0); PG8_LDB(B1, 0, 1); PG8_SCHED; PG8_LDA(At, 0, 0); PG8_STAGE(PG8_SA(1, 1), a1 + hstep, voffA);
;             PG8_WAIT_V(8); PG8_WAIT_L(0); PG8_BAR; PG8_MMA(0, 0, At, B0); PG8_MMA(0, 1, At, B1); PG8_BAR; PG8_SCHED;
;             PG8_LDA(At, 0, 1); PG8_STAGE(PG8_SB(0, 0), b2, voffB); PG8_STAGE(PG8_SB(0, 1), b2 + hstep, voffB); PG8_STAGE(PG8_SA(0, 0), a2, voffA);
;             PG8_WAIT_V(8); PG8_WAIT_L(0); PG8_BAR; PG8_MMA(1, 0, At, B0); PG8_MMA(1, 1, At, B1); PG8_BAR; PG8_SCHED;
.LBB0_139:
	ds_read_b128 v[2:5], v187
	ds_read_b128 v[6:9], v187 offset:1024
	ds_read_b128 v[138:141], v187 offset:2048
	ds_read_b128 v[142:145], v187 offset:3072
	ds_read_b128 v[146:149], v197
	ds_read_b128 v[150:153], v197 offset:1024
	ds_read_b128 v[154:157], v197 offset:2048
	ds_read_b128 v[158:161], v197 offset:3072
	s_add_u32 s14, s12, 0xfff00080
	s_addc_u32 s15, s13, -1
	s_cmp_eq_u32 s33, 60
	s_cselect_b32 s17, s2, s15
	s_cselect_b32 s16, s11, s14
	s_cselect_b32 s15, s26, s30
	s_cselect_b32 s14, s28, s29
	s_add_i32 m0, s27, 0xc000
	ds_read_b128 v[202:205], v199
	ds_read_b128 v[206:209], v199 offset:1024
	ds_read_b128 v[214:217], v199 offset:2048
	ds_read_b128 v[218:221], v199 offset:3072
	ds_read_b128 v[222:225], v199 offset:4096
	ds_read_b128 v[226:229], v199 offset:5120
	ds_read_b128 v[230:233], v199 offset:6144
	ds_read_b128 v[234:237], v199 offset:7168
	global_load_lds_dwordx4 v188, s[12:13]
	s_add_i32 m0, s27, 0xe000
	s_nop 0
	global_load_lds_dwordx4 v190, s[12:13]
	s_waitcnt vmcnt(8)
	s_waitcnt lgkmcnt(0)
	s_setprio 1
	s_barrier
	v_mfma_f32_16x16x32_bf16 v[134:137], v[2:5], v[202:205], v[134:137]
	v_mfma_f32_16x16x32_bf16 v[134:137], v[6:9], v[206:209], v[134:137]
	v_mfma_f32_16x16x32_bf16 v[118:121], v[6:9], v[218:221], v[118:121]
	v_mfma_f32_16x16x32_bf16 v[118:121], v[2:5], v[214:217], v[118:121]
	v_mfma_f32_16x16x32_bf16 v[102:105], v[2:5], v[222:225], v[102:105]
	v_mfma_f32_16x16x32_bf16 v[102:105], v[6:9], v[226:229], v[102:105]
	v_mfma_f32_16x16x32_bf16 v[86:89], v[6:9], v[234:237], v[86:89]
	v_mfma_f32_16x16x32_bf16 v[86:89], v[2:5], v[230:233], v[86:89]
	v_mfma_f32_16x16x32_bf16 v[82:85], v[138:141], v[230:233], v[82:85]
	v_mfma_f32_16x16x32_bf16 v[82:85], v[142:145], v[234:237], v[82:85]
	v_mfma_f32_16x16x32_bf16 v[130:133], v[142:145], v[206:209], v[130:133]
	v_mfma_f32_16x16x32_bf16 v[130:133], v[138:141], v[202:205], v[130:133]
	v_mfma_f32_16x16x32_bf16 v[114:117], v[138:141], v[214:217], v[114:117]
	v_mfma_f32_16x16x32_bf16 v[114:117], v[142:145], v[218:221], v[114:117]
	v_mfma_f32_16x16x32_bf16 v[98:101], v[142:145], v[226:229], v[98:101]
	v_mfma_f32_16x16x32_bf16 v[98:101], v[138:141], v[222:225], v[98:101]
	s_setprio 0
	s_setprio 1
	v_mfma_f32_16x16x32_bf16 v[94:97], v[146:149], v[222:225], v[94:97]
	v_mfma_f32_16x16x32_bf16 v[94:97], v[150:153], v[226:229], v[94:97]
	v_mfma_f32_16x16x32_bf16 v[126:129], v[150:153], v[206:209], v[126:129]
	v_mfma_f32_16x16x32_bf16 v[126:129], v[146:149], v[202:205], v[126:129]
	v_mfma_f32_16x16x32_bf16 v[110:113], v[146:149], v[214:217], v[110:113]
	v_mfma_f32_16x16x32_bf16 v[110:113], v[150:153], v[218:221], v[110:113]
	v_mfma_f32_16x16x32_bf16 v[78:81], v[150:153], v[234:237], v[78:81]
	v_mfma_f32_16x16x32_bf16 v[78:81], v[146:149], v[230:233], v[78:81]
	v_mfma_f32_16x16x32_bf16 v[74:77], v[154:157], v[230:233], v[74:77]
	v_mfma_f32_16x16x32_bf16 v[74:77], v[158:161], v[234:237], v[74:77]
	v_mfma_f32_16x16x32_bf16 v[122:125], v[158:161], v[206:209], v[122:125]
	v_mfma_f32_16x16x32_bf16 v[122:125], v[154:157], v[202:205], v[122:125]
	v_mfma_f32_16x16x32_bf16 v[106:109], v[154:157], v[214:217], v[106:109]
	v_mfma_f32_16x16x32_bf16 v[106:109], v[158:161], v[218:221], v[106:109]
	v_mfma_f32_16x16x32_bf16 v[90:93], v[158:161], v[226:229], v[90:93]
	v_mfma_f32_16x16x32_bf16 v[90:93], v[154:157], v[222:225], v[90:93]
	s_barrier
	s_setprio 0
	s_add_i32 s34, s41, s25
	s_mov_b32 m0, s34
	ds_read_b128 v[202:205], v199 offset:16384
	ds_read_b128 v[206:209], v199 offset:17408
	ds_read_b128 v[214:217], v199 offset:18432
	ds_read_b128 v[218:221], v199 offset:19456
	ds_read_b128 v[222:225], v199 offset:20480
	ds_read_b128 v[226:229], v199 offset:21504
	ds_read_b128 v[230:233], v199 offset:22528
	ds_read_b128 v[234:237], v199 offset:23552
	global_load_lds_dwordx4 v168, s[14:15]
	s_add_i32 m0, s34, 0x2000
	s_add_u32 s34, s14, 0x100000
	s_addc_u32 s35, s15, 0
	s_add_i32 s79, s92, s25
	global_load_lds_dwordx4 v172, s[14:15]
	s_mov_b32 m0, s79
	v_lshl_add_u64 v[240:241], s[16:17], 0, v[170:171]
	global_load_lds_dwordx4 v168, s[34:35]
	s_add_i32 m0, s79, 0x2000
	s_nop 0
	global_load_lds_dwordx4 v172, s[34:35]
	v_lshl_add_u64 v[238:239], s[16:17], 0, v[164:165]
	s_mov_b32 m0, s27
	s_nop 0
	global_load_lds_dwordx4 v164, s[16:17]
	s_mov_b32 m0, s39
	s_nop 0
	global_load_lds_dwordx4 v170, s[16:17]
	s_waitcnt vmcnt(8)
	s_waitcnt lgkmcnt(0)
	s_setprio 1
	s_barrier
	v_mfma_f32_16x16x32_bf16 v[70:73], v[6:9], v[206:209], v[70:73]
	v_mfma_f32_16x16x32_bf16 v[70:73], v[2:5], v[202:205], v[70:73]
	v_mfma_f32_16x16x32_bf16 v[54:57], v[2:5], v[214:217], v[54:57]
	v_mfma_f32_16x16x32_bf16 v[54:57], v[6:9], v[218:221], v[54:57]
	v_mfma_f32_16x16x32_bf16 v[38:41], v[6:9], v[226:229], v[38:41]
	v_mfma_f32_16x16x32_bf16 v[38:41], v[2:5], v[222:225], v[38:41]
	v_mfma_f32_16x16x32_bf16 v[2:5], v[2:5], v[230:233], v[22:25]
	v_mfma_f32_16x16x32_bf16 v[2:5], v[6:9], v[234:237], v[2:5]
	v_mfma_f32_16x16x32_bf16 v[6:9], v[142:145], v[234:237], v[18:21]
	v_mfma_f32_16x16x32_bf16 v[6:9], v[138:141], v[230:233], v[6:9]
	v_mfma_f32_16x16x32_bf16 v[66:69], v[138:141], v[202:205], v[66:69]
	v_mfma_f32_16x16x32_bf16 v[66:69], v[142:145], v[206:209], v[66:69]
	v_mfma_f32_16x16x32_bf16 v[50:53], v[142:145], v[218:221], v[50:53]
	v_mfma_f32_16x16x32_bf16 v[50:53], v[138:141], v[214:217], v[50:53]
	v_mfma_f32_16x16x32_bf16 v[34:37], v[138:141], v[222:225], v[34:37]
	v_mfma_f32_16x16x32_bf16 v[34:37], v[142:145], v[226:229], v[34:37]
	s_setprio 0
	s_setprio 1
	v_mfma_f32_16x16x32_bf16 v[18:21], v[150:153], v[226:229], v[30:33]
	v_mfma_f32_16x16x32_bf16 v[30:33], v[146:149], v[222:225], v[18:21]
	v_mfma_f32_16x16x32_bf16 v[14:17], v[146:149], v[230:233], v[14:17]
	v_mfma_f32_16x16x32_bf16 v[14:17], v[150:153], v[234:237], v[14:17]
	v_mfma_f32_16x16x32_bf16 v[18:21], v[150:153], v[206:209], v[62:65]
	v_mfma_f32_16x16x32_bf16 v[62:65], v[146:149], v[202:205], v[18:21]
	v_mfma_f32_16x16x32_bf16 v[18:21], v[146:149], v[214:217], v[46:49]
	v_mfma_f32_16x16x32_bf16 v[46:49], v[150:153], v[218:221], v[18:21]
	v_mfma_f32_16x16x32_bf16 v[18:21], v[158:161], v[218:221], v[42:45]
	v_mfma_f32_16x16x32_bf16 v[42:45], v[154:157], v[214:217], v[18:21]
	v_mfma_f32_16x16x32_bf16 v[18:21], v[154:157], v[222:225], v[26:29]
	v_mfma_f32_16x16x32_bf16 v[26:29], v[158:161], v[226:229], v[18:21]
	v_mfma_f32_16x16x32_bf16 v[10:13], v[158:161], v[234:237], v[10:13]
	v_mfma_f32_16x16x32_bf16 v[10:13], v[154:157], v[230:233], v[10:13]
	v_mfma_f32_16x16x32_bf16 v[18:21], v[154:157], v[202:205], v[58:61]
	v_mfma_f32_16x16x32_bf16 v[58:61], v[158:161], v[206:209], v[18:21]
	s_barrier
; #define PG8_STAGE(bufoff, gbase, voff) do { _Pragma("unroll") for (int _i = 0; _i < 2; ++_i) \
;         __builtin_amdgcn_global_load_lds((const unsigned*)((const char*)(gbase) + (voff)[_i]), (PG8_LAS unsigned*)(lds + (bufoff) + ldsw + _i * 8192), 16, 0, 0); } while (0)
; #define PG8_LDA(dst, b, h) do { _Pragma("unroll") for (int m = 0; m < 4; ++m) _Pragma("unroll") for (int k = 0; k < 2; ++k) dst[m][k] = *(const PG8_LAS bf16x8*)(lds + PG8_SA(b, h) + aoff + m * 2048 + k * 1024); } while (0)
; #define PG8_LDB(dst, b, h) do { _Pragma("unroll") for (int n = 0; n < 2; ++n) _Pragma("unroll") for (int k = 0; k < 2; ++k) dst[n][k] = *(const PG8_LAS bf16x8*)(lds + PG8_SB(b, h) + boff + n * 2048 + k * 1024); } while (0)
; #define PG8_MMA(ai, bj, At, Bt) do { __builtin_amdgcn_s_setprio(1); _Pragma("unroll") for (int m = 0; m < 4; ++m) _Pragma("unroll") for (int n = 0; n < 2; ++n) _Pragma("unroll") for (int k = 0; k < 2; ++k) \
;         acc[ai][bj][m][n] = __builtin_amdgcn_mfma_f32_16x16x32_bf16(Bt[n][k], At[m][k], acc[ai][bj][m][n], 0, 0, 0); __builtin_amdgcn_s_setprio(0); } while (0)
; #define PG8_WAIT_V(n) asm volatile("s_waitcnt vmcnt(" #n ")" ::: "memory")
; #define PG8_WAIT_L(n) asm volatile("s_waitcnt lgkmcnt(" #n ")" ::: "memory")
; #define PG8_BAR __builtin_amdgcn_s_barrier()
; #define PG8_SCHED __builtin_amdgcn_sched_barrier(0)
; template <class Epi, class Sched, bool ALIGN_EPI = false, bool SP2 = false>
; __device__ __forceinline__ void gemm_phase(PG8_LAS unsigned char* lds, const Gemm g, const Sched& S, const Epi& E) {
;     ...
;         for (int t = 0; t < nt; t += 2) {
;     ...
;             PG8_LDB(B0, 1, 0); PG8_LDB(B1, 1, 1); PG8_SCHED; PG8_LDA(At, 1, 0); PG8_STAGE(PG8_SA(0, 1), a2 + hstep, voffA);
;             PG8_WAIT_V(8); PG8_WAIT_L(0); PG8_BAR; PG8_MMA(0, 0, At, B0); PG8_MMA(0, 1, At, B1); PG8_BAR; PG8_SCHED;
;             PG8_LDA(At, 1, 1); PG8_STAGE(PG8_SB(1, 0), b3, voffB); PG8_STAGE(PG8_SB(1, 1), b3 + hstep, voffB); PG8_STAGE(PG8_SA(1, 0), a3, voffA);
;             PG8_WAIT_V(8); PG8_WAIT_L(0); PG8_BAR; PG8_MMA(1, 0, At, B0); PG8_MMA(1, 1, At, B1); PG8_BAR; PG8_SCHED;
	s_setprio 0
	s_add_i32 s34, 0, 0x18000
	s_add_i32 s35, 0, 0x1c000
	v_add_u32_e32 v142, s34, v179
	v_add_u32_e32 v158, s35, v179
	ds_read_b128 v[18:21], v142
	ds_read_b128 v[22:25], v142 offset:1024
	ds_read_b128 v[138:141], v142 offset:2048
	ds_read_b128 v[142:145], v142 offset:3072
	ds_read_b128 v[146:149], v158
	ds_read_b128 v[150:153], v158 offset:1024
	ds_read_b128 v[154:157], v158 offset:2048
	ds_read_b128 v[158:161], v158 offset:3072
	s_add_u32 s16, s16, 0x100000
	s_addc_u32 s17, s17, 0
	s_mov_b32 m0, s71
	ds_read_b128 v[202:205], v199 offset:32768
	ds_read_b128 v[206:209], v199 offset:33792
	ds_read_b128 v[214:217], v199 offset:34816
	ds_read_b128 v[218:221], v199 offset:35840
	ds_read_b128 v[222:225], v199 offset:36864
	ds_read_b128 v[226:229], v199 offset:37888
	ds_read_b128 v[230:233], v199 offset:38912
	ds_read_b128 v[234:237], v199 offset:39936
	global_load_lds_dwordx4 v164, s[16:17]
	s_mov_b32 m0, s87
	s_nop 0
	global_load_lds_dwordx4 v170, s[16:17]
	s_waitcnt vmcnt(8)
	s_waitcnt lgkmcnt(0)
	s_setprio 1
	s_barrier
	v_mfma_f32_16x16x32_bf16 v[134:137], v[18:21], v[202:205], v[134:137]
	v_mfma_f32_16x16x32_bf16 v[134:137], v[22:25], v[206:209], v[134:137]
	v_mfma_f32_16x16x32_bf16 v[118:121], v[22:25], v[218:221], v[118:121]
	v_mfma_f32_16x16x32_bf16 v[118:121], v[18:21], v[214:217], v[118:121]
	v_mfma_f32_16x16x32_bf16 v[102:105], v[18:21], v[222:225], v[102:105]
	v_mfma_f32_16x16x32_bf16 v[102:105], v[22:25], v[226:229], v[102:105]
	v_mfma_f32_16x16x32_bf16 v[86:89], v[22:25], v[234:237], v[86:89]
	v_mfma_f32_16x16x32_bf16 v[86:89], v[18:21], v[230:233], v[86:89]
	v_mfma_f32_16x16x32_bf16 v[82:85], v[138:141], v[230:233], v[82:85]
	v_mfma_f32_16x16x32_bf16 v[82:85], v[142:145], v[234:237], v[82:85]
	v_mfma_f32_16x16x32_bf16 v[130:133], v[142:145], v[206:209], v[130:133]
	v_mfma_f32_16x16x32_bf16 v[130:133], v[138:141], v[202:205], v[130:133]
	v_mfma_f32_16x16x32_bf16 v[114:117], v[138:141], v[214:217], v[114:117]
	v_mfma_f32_16x16x32_bf16 v[114:117], v[142:145], v[218:221], v[114:117]
	v_mfma_f32_16x16x32_bf16 v[98:101], v[142:145], v[226:229], v[98:101]
	v_mfma_f32_16x16x32_bf16 v[98:101], v[138:141], v[222:225], v[98:101]
	s_setprio 0
	s_setprio 1
	v_mfma_f32_16x16x32_bf16 v[94:97], v[146:149], v[222:225], v[94:97]
	v_mfma_f32_16x16x32_bf16 v[94:97], v[150:153], v[226:229], v[94:97]
	v_mfma_f32_16x16x32_bf16 v[126:129], v[150:153], v[206:209], v[126:129]
	v_mfma_f32_16x16x32_bf16 v[126:129], v[146:149], v[202:205], v[126:129]
	v_mfma_f32_16x16x32_bf16 v[110:113], v[146:149], v[214:217], v[110:113]
	v_mfma_f32_16x16x32_bf16 v[110:113], v[150:153], v[218:221], v[110:113]
	v_mfma_f32_16x16x32_bf16 v[78:81], v[150:153], v[234:237], v[78:81]
	v_mfma_f32_16x16x32_bf16 v[78:81], v[146:149], v[230:233], v[78:81]
	v_mfma_f32_16x16x32_bf16 v[74:77], v[154:157], v[230:233], v[74:77]
	v_mfma_f32_16x16x32_bf16 v[74:77], v[158:161], v[234:237], v[74:77]
	v_mfma_f32_16x16x32_bf16 v[122:125], v[158:161], v[206:209], v[122:125]
	v_mfma_f32_16x16x32_bf16 v[122:125], v[154:157], v[202:205], v[122:125]
	v_mfma_f32_16x16x32_bf16 v[106:109], v[154:157], v[214:217], v[106:109]
	v_mfma_f32_16x16x32_bf16 v[106:109], v[158:161], v[218:221], v[106:109]
	v_mfma_f32_16x16x32_bf16 v[90:93], v[158:161], v[226:229], v[90:93]
	v_mfma_f32_16x16x32_bf16 v[90:93], v[154:157], v[222:225], v[90:93]
	s_barrier
	s_setprio 0
	s_add_i32 s16, s34, s25
	s_add_u32 s98, s14, s46
	s_addc_u32 s99, s15, s47
	s_mov_b32 m0, s16
	ds_read_b128 v[202:205], v199 offset:49152
	ds_read_b128 v[206:209], v199 offset:50176
	ds_read_b128 v[214:217], v199 offset:51200
	ds_read_b128 v[218:221], v199 offset:52224
	ds_read_b128 v[222:225], v199 offset:53248
	ds_read_b128 v[226:229], v199 offset:54272
	ds_read_b128 v[230:233], v199 offset:55296
	ds_read_b128 v[234:237], v199 offset:56320
	global_load_lds_dwordx4 v168, s[98:99]
	s_add_i32 m0, s16, 0x2000
	s_add_u32 s14, s14, 0x100080
	s_addc_u32 s15, s15, 0
	s_add_i32 s16, s35, s25
	global_load_lds_dwordx4 v172, s[98:99]
	s_mov_b32 m0, s16
	s_nop 0
	global_load_lds_dwordx4 v168, s[14:15]
	s_add_i32 m0, s16, 0x2000
	s_nop 0
	global_load_lds_dwordx4 v172, s[14:15]
	v_lshl_add_u64 v[162:163], v[238:239], 0, s[46:47]
	s_mov_b32 m0, s95
	s_nop 0
	global_load_lds_dwordx4 v[162:163], off
	v_lshl_add_u64 v[162:163], v[240:241], 0, s[46:47]
	s_mov_b32 m0, s96
	s_nop 0
	global_load_lds_dwordx4 v[162:163], off
	s_waitcnt vmcnt(8)
	s_waitcnt lgkmcnt(0)
	s_setprio 1
	s_barrier
	v_mfma_f32_16x16x32_bf16 v[70:73], v[18:21], v[202:205], v[70:73]
	v_mfma_f32_16x16x32_bf16 v[70:73], v[22:25], v[206:209], v[70:73]
	v_mfma_f32_16x16x32_bf16 v[54:57], v[22:25], v[218:221], v[54:57]
	v_mfma_f32_16x16x32_bf16 v[54:57], v[18:21], v[214:217], v[54:57]
	v_mfma_f32_16x16x32_bf16 v[38:41], v[18:21], v[222:225], v[38:41]
	v_mfma_f32_16x16x32_bf16 v[38:41], v[22:25], v[226:229], v[38:41]
	v_mfma_f32_16x16x32_bf16 v[2:5], v[22:25], v[234:237], v[2:5]
	v_mfma_f32_16x16x32_bf16 v[22:25], v[18:21], v[230:233], v[2:5]
	v_mfma_f32_16x16x32_bf16 v[2:5], v[138:141], v[230:233], v[6:9]
	v_mfma_f32_16x16x32_bf16 v[18:21], v[142:145], v[234:237], v[2:5]
	v_mfma_f32_16x16x32_bf16 v[66:69], v[142:145], v[206:209], v[66:69]
	v_mfma_f32_16x16x32_bf16 v[66:69], v[138:141], v[202:205], v[66:69]
	v_mfma_f32_16x16x32_bf16 v[50:53], v[138:141], v[214:217], v[50:53]
	v_mfma_f32_16x16x32_bf16 v[50:53], v[142:145], v[218:221], v[50:53]
	v_mfma_f32_16x16x32_bf16 v[34:37], v[142:145], v[226:229], v[34:37]
	v_mfma_f32_16x16x32_bf16 v[34:37], v[138:141], v[222:225], v[34:37]
	s_setprio 0
	s_setprio 1
	v_mfma_f32_16x16x32_bf16 v[2:5], v[146:149], v[222:225], v[30:33]
	v_mfma_f32_16x16x32_bf16 v[30:33], v[150:153], v[226:229], v[2:5]
	v_mfma_f32_16x16x32_bf16 v[2:5], v[150:153], v[234:237], v[14:17]
	v_mfma_f32_16x16x32_bf16 v[14:17], v[146:149], v[230:233], v[2:5]
	v_mfma_f32_16x16x32_bf16 v[2:5], v[146:149], v[202:205], v[62:65]
	v_mfma_f32_16x16x32_bf16 v[62:65], v[150:153], v[206:209], v[2:5]
	v_mfma_f32_16x16x32_bf16 v[2:5], v[150:153], v[218:221], v[46:49]
	v_mfma_f32_16x16x32_bf16 v[46:49], v[146:149], v[214:217], v[2:5]
	v_mfma_f32_16x16x32_bf16 v[2:5], v[154:157], v[214:217], v[42:45]
	v_mfma_f32_16x16x32_bf16 v[42:45], v[158:161], v[218:221], v[2:5]
	v_mfma_f32_16x16x32_bf16 v[2:5], v[158:161], v[226:229], v[26:29]
	v_mfma_f32_16x16x32_bf16 v[26:29], v[154:157], v[222:225], v[2:5]
	v_mfma_f32_16x16x32_bf16 v[2:5], v[154:157], v[230:233], v[10:13]
	v_mfma_f32_16x16x32_bf16 v[10:13], v[158:161], v[234:237], v[2:5]
	v_mfma_f32_16x16x32_bf16 v[2:5], v[158:161], v[206:209], v[58:61]
	v_mfma_f32_16x16x32_bf16 v[58:61], v[154:157], v[202:205], v[2:5]
	s_barrier
	s_setprio 0
	s_add_i32 s33, s33, 2
	s_add_u32 s12, s12, 0x100
	s_addc_u32 s13, s13, 0
	s_add_u32 s29, s29, 0x100
	s_addc_u32 s30, s30, 0
	s_cmp_gt_u32 s33, 61
	s_cbranch_scc0 .LBB0_139
	s_and_b64 vcc, exec, s[48:49]
	s_cbranch_vccz .LBB0_142
	s_barrier

; #define PG8_STAGE(bufoff, gbase, voff) do { _Pragma("unroll") for (int _i = 0; _i < 2; ++_i) \
;         __builtin_amdgcn_global_load_lds((const unsigned*)((const char*)(gbase) + (voff)[_i]), (PG8_LAS unsigned*)(lds + (bufoff) + ldsw + _i * 8192), 16, 0, 0); } while (0)
; #define PG8_LDA(dst, b, h) do { _Pragma("unroll") for (int m = 0; m < 4; ++m) _Pragma("unroll") for (int k = 0; k < 2; ++k) dst[m][k] = *(const PG8_LAS bf16x8*)(lds + PG8_SA(b, h) + aoff + m * 2048 + k * 1024); } while (0)
; #define PG8_LDB(dst, b, h) do { _Pragma("unroll") for (int n = 0; n < 2; ++n) _Pragma("unroll") for (int k = 0; k < 2; ++k) dst[n][k] = *(const PG8_LAS bf16x8*)(lds + PG8_SB(b, h) + boff + n * 2048 + k * 1024); } while (0)
; #define PG8_MMA(ai, bj, At, Bt) do { __builtin_amdgcn_s_setprio(1); _Pragma("unroll") for (int m = 0; m < 4; ++m) _Pragma("unroll") for (int n = 0; n < 2; ++n) _Pragma("unroll") for (int k = 0; k < 2; ++k) \
;         acc[ai][bj][m][n] = __builtin_amdgcn_mfma_f32_16x16x32_bf16(Bt[n][k], At[m][k], acc[ai][bj][m][n], 0, 0, 0); __builtin_amdgcn_s_setprio(0); } while (0)
; #define PG8_WAIT_V(n) asm volatile("s_waitcnt vmcnt(" #n ")" ::: "memory")
; #define PG8_WAIT_L(n) asm volatile("s_waitcnt lgkmcnt(" #n ")" ::: "memory")
; template <class Epi, class Sched, bool ALIGN_EPI = false, bool SP2 = false>
; __device__ __forceinline__ void gemm_phase(PG8_LAS unsigned char* lds, const Gemm g, const Sched& S, const Epi& E) {
;     ...
;             const bool last = (t == nt - 2);
;             const char* a1 = cA + (size_t)(t + 1) * kstep;
;             const char* a2 = last ? nA : cA + (size_t)(t + 2) * kstep; const char* b2 = last ? nB : cB + (size_t)(t + 2) * kstep;
;             const char* a3 = a2 + kstep; const char* b3 = b2 + kstep;
;             if (last && has_next) S.a_ready(nxt);
;             if constexpr (SP2) {
;             PG8_LDB(B0, 0, 0); PG8_LDB(B1, 0, 1); PG8_SCHED; PG8_LDA(At, 0, 0); PG8_STAGE(PG8_SA(1, 1), a1 + hstep, voffA);
;             PG8_WAIT_V(8); PG8_WAIT_L(0); PG8_BAR; PG8_MMA(0, 0, At, B0); PG8_MMA(0, 1, At, B1); PG8_BAR; PG8_SCHED;
;             PG8_LDA(At, 0, 1); PG8_STAGE(PG8_SB(0, 0), b2, voffB); PG8_STAGE(PG8_SB(0, 1), b2 + hstep, voffB); PG8_STAGE(PG8_SA(0, 0), a2, voffA);
;             PG8_WAIT_V(8); PG8_WAIT_L(0); PG8_BAR; PG8_MMA(1, 0, At, B0); PG8_MMA(1, 1, At, B1); PG8_BAR; PG8_SCHED;
.LBB0_592:
	s_or_b32 s10, s52, 1
	s_lshl_b64 s[96:97], s[10:11], 7
	s_add_i32 s10, s52, 2
	s_lshl_b64 s[54:55], s[10:11], 7
	s_cmp_lg_u32 s52, s94
	s_cselect_b32 s52, s54, 0
	s_cselect_b32 s53, s55, 0
	s_add_u32 s54, s50, s52
	s_addc_u32 s55, s51, s53
	s_add_i32 s95, 0, 0x10000
	v_add_u32_e32 v87, s95, v85
	ds_read_b128 v[88:91], v87
	ds_read_b128 v[92:95], v87 offset:1024
	ds_read_b128 v[100:103], v87 offset:2048
	ds_read_b128 v[104:107], v87 offset:3072
	s_add_u32 s52, s48, s52
	s_addc_u32 s53, s49, s53
	s_add_u32 s96, s50, s96
	s_addc_u32 s97, s51, s97
	s_add_u32 s96, s96, 0x100000
	s_addc_u32 s97, s97, 0
	s_add_i32 m0, s17, 0xc000
	ds_read_b128 v[108:111], v86
	ds_read_b128 v[112:115], v86 offset:1024
	ds_read_b128 v[116:119], v86 offset:2048
	ds_read_b128 v[120:123], v86 offset:3072
	ds_read_b128 v[124:127], v86 offset:4096
	ds_read_b128 v[128:131], v86 offset:5120
	ds_read_b128 v[132:135], v86 offset:6144
	ds_read_b128 v[136:139], v86 offset:7168
	global_load_lds_dwordx4 v66, s[96:97]
	s_add_i32 m0, s17, 0xe000
	s_nop 0
	global_load_lds_dwordx4 v76, s[96:97]
	s_waitcnt vmcnt(8)
	s_waitcnt lgkmcnt(0)
	s_setprio 1
	s_barrier
	v_mfma_f32_16x16x32_bf16 v[62:65], v[88:91], v[108:111], v[62:65]
	v_mfma_f32_16x16x32_bf16 v[62:65], v[92:95], v[112:115], v[62:65]
	v_mfma_f32_16x16x32_bf16 v[54:57], v[92:95], v[120:123], v[54:57]
	v_mfma_f32_16x16x32_bf16 v[54:57], v[88:91], v[116:119], v[54:57]
	v_mfma_f32_16x16x32_bf16 v[46:49], v[88:91], v[124:127], v[46:49]
	v_mfma_f32_16x16x32_bf16 v[46:49], v[92:95], v[128:131], v[46:49]
	v_mfma_f32_16x16x32_bf16 v[38:41], v[92:95], v[136:139], v[38:41]
	v_mfma_f32_16x16x32_bf16 v[38:41], v[88:91], v[132:135], v[38:41]
	v_mfma_f32_16x16x32_bf16 v[34:37], v[100:103], v[132:135], v[34:37]
	v_mfma_f32_16x16x32_bf16 v[34:37], v[104:107], v[136:139], v[34:37]
	v_mfma_f32_16x16x32_bf16 v[58:61], v[104:107], v[112:115], v[58:61]
	v_mfma_f32_16x16x32_bf16 v[58:61], v[100:103], v[108:111], v[58:61]
	v_mfma_f32_16x16x32_bf16 v[50:53], v[100:103], v[116:119], v[50:53]
	v_mfma_f32_16x16x32_bf16 v[50:53], v[104:107], v[120:123], v[50:53]
	v_mfma_f32_16x16x32_bf16 v[42:45], v[104:107], v[128:131], v[42:45]
	v_mfma_f32_16x16x32_bf16 v[42:45], v[100:103], v[124:127], v[42:45]
	s_setprio 0
	s_setprio 1
	s_setprio 0
	s_barrier
	s_add_i32 s95, s95, s29
	s_mov_b32 m0, s95
	ds_read_b128 v[108:111], v86 offset:16384
	ds_read_b128 v[112:115], v86 offset:17408
	ds_read_b128 v[116:119], v86 offset:18432
	ds_read_b128 v[120:123], v86 offset:19456
	ds_read_b128 v[124:127], v86 offset:20480
	ds_read_b128 v[128:131], v86 offset:21504
	ds_read_b128 v[132:135], v86 offset:22528
	ds_read_b128 v[136:139], v86 offset:23552
	global_load_lds_dwordx4 v78, s[52:53]
	s_add_i32 m0, s95, 0x2000
	s_add_u32 s96, s52, 0x100000
	s_addc_u32 s97, s53, 0
	global_load_lds_dwordx4 v74, s[52:53]
	s_mov_b32 m0, s30
	v_lshl_add_u64 v[144:145], s[54:55], 0, v[76:77]
	global_load_lds_dwordx4 v78, s[96:97]
	s_mov_b32 m0, s33
	s_nop 0
	global_load_lds_dwordx4 v74, s[96:97]
	v_lshl_add_u64 v[142:143], s[54:55], 0, v[66:67]
	s_mov_b32 m0, s17
	s_nop 0
	global_load_lds_dwordx4 v66, s[54:55]
	s_mov_b32 m0, s34
	s_nop 0
	global_load_lds_dwordx4 v76, s[54:55]
	s_waitcnt vmcnt(8)
	s_waitcnt lgkmcnt(0)
	s_setprio 1
	s_barrier
	v_mfma_f32_16x16x32_bf16 v[30:33], v[88:91], v[108:111], v[30:33]
	v_mfma_f32_16x16x32_bf16 v[30:33], v[92:95], v[112:115], v[30:33]
	v_mfma_f32_16x16x32_bf16 v[22:25], v[92:95], v[120:123], v[22:25]
	v_mfma_f32_16x16x32_bf16 v[22:25], v[88:91], v[116:119], v[22:25]
	v_mfma_f32_16x16x32_bf16 v[14:17], v[88:91], v[124:127], v[14:17]
	v_mfma_f32_16x16x32_bf16 v[14:17], v[92:95], v[128:131], v[14:17]
	v_mfma_f32_16x16x32_bf16 v[6:9], v[92:95], v[136:139], v[6:9]
	v_mfma_f32_16x16x32_bf16 v[6:9], v[88:91], v[132:135], v[6:9]
	v_mfma_f32_16x16x32_bf16 v[2:5], v[100:103], v[132:135], v[2:5]
	v_mfma_f32_16x16x32_bf16 v[2:5], v[104:107], v[136:139], v[2:5]
	v_mfma_f32_16x16x32_bf16 v[26:29], v[104:107], v[112:115], v[26:29]
	v_mfma_f32_16x16x32_bf16 v[26:29], v[100:103], v[108:111], v[26:29]
	v_mfma_f32_16x16x32_bf16 v[18:21], v[100:103], v[116:119], v[18:21]
	v_mfma_f32_16x16x32_bf16 v[18:21], v[104:107], v[120:123], v[18:21]
	v_mfma_f32_16x16x32_bf16 v[10:13], v[104:107], v[128:131], v[10:13]
	v_mfma_f32_16x16x32_bf16 v[10:13], v[100:103], v[124:127], v[10:13]
	s_setprio 0
	s_setprio 1
	s_setprio 0
	s_barrier
; #define PG8_STAGE(bufoff, gbase, voff) do { _Pragma("unroll") for (int _i = 0; _i < 2; ++_i) \
;         __builtin_amdgcn_global_load_lds((const unsigned*)((const char*)(gbase) + (voff)[_i]), (PG8_LAS unsigned*)(lds + (bufoff) + ldsw + _i * 8192), 16, 0, 0); } while (0)
; #define PG8_LDA(dst, b, h) do { _Pragma("unroll") for (int m = 0; m < 4; ++m) _Pragma("unroll") for (int k = 0; k < 2; ++k) dst[m][k] = *(const PG8_LAS bf16x8*)(lds + PG8_SA(b, h) + aoff + m * 2048 + k * 1024); } while (0)
; #define PG8_LDB(dst, b, h) do { _Pragma("unroll") for (int n = 0; n < 2; ++n) _Pragma("unroll") for (int k = 0; k < 2; ++k) dst[n][k] = *(const PG8_LAS bf16x8*)(lds + PG8_SB(b, h) + boff + n * 2048 + k * 1024); } while (0)
; #define PG8_MMA(ai, bj, At, Bt) do { __builtin_amdgcn_s_setprio(1); _Pragma("unroll") for (int m = 0; m < 4; ++m) _Pragma("unroll") for (int n = 0; n < 2; ++n) _Pragma("unroll") for (int k = 0; k < 2; ++k) \
;         acc[ai][bj][m][n] = __builtin_amdgcn_mfma_f32_16x16x32_bf16(Bt[n][k], At[m][k], acc[ai][bj][m][n], 0, 0, 0); __builtin_amdgcn_s_setprio(0); } while (0)
; #define PG8_WAIT_V(n) asm volatile("s_waitcnt vmcnt(" #n ")" ::: "memory")
; #define PG8_WAIT_L(n) asm volatile("s_waitcnt lgkmcnt(" #n ")" ::: "memory")
; #define PG8_BAR __builtin_amdgcn_s_barrier()
; #define PG8_SCHED __builtin_amdgcn_sched_barrier(0)
; template <class Epi, class Sched, bool ALIGN_EPI = false, bool SP2 = false>
; __device__ __forceinline__ void gemm_phase(PG8_LAS unsigned char* lds, const Gemm g, const Sched& S, const Epi& E) {
;     ...
;             PG8_LDB(B0, 1, 0); PG8_LDB(B1, 1, 1); PG8_SCHED; PG8_LDA(At, 1, 0); PG8_STAGE(PG8_SA(0, 1), a2 + hstep, voffA);
;             PG8_WAIT_V(8); PG8_WAIT_L(0); PG8_BAR; PG8_MMA(0, 0, At, B0); PG8_MMA(0, 1, At, B1); PG8_BAR; PG8_SCHED;
;             PG8_LDA(At, 1, 1); PG8_STAGE(PG8_SB(1, 0), b3, voffB); PG8_STAGE(PG8_SB(1, 1), b3 + hstep, voffB); PG8_STAGE(PG8_SA(1, 0), a3, voffA);
;             PG8_WAIT_V(8); PG8_WAIT_L(0); PG8_BAR; PG8_MMA(1, 0, At, B0); PG8_MMA(1, 1, At, B1); PG8_BAR; PG8_SCHED;
;     ...
;         if constexpr (ALIGN_EPI) { if (wr == 0) PG8_BAR; }
;         if constexpr (!Epi::AFTER_DRAIN) { E(acc, cur, wr, wc, fr, fq); S.done(cur); }
;         if (!has_next) break;
	s_add_i32 s95, 0, 0x18000
	v_add_u32_e32 v87, s95, v85
	ds_read_b128 v[88:91], v87
	ds_read_b128 v[92:95], v87 offset:1024
	ds_read_b128 v[100:103], v87 offset:2048
	ds_read_b128 v[104:107], v87 offset:3072
	s_add_u32 s54, s54, 0x100000
	s_addc_u32 s55, s55, 0
	s_mov_b32 m0, s35
	ds_read_b128 v[108:111], v86 offset:32768
	ds_read_b128 v[112:115], v86 offset:33792
	ds_read_b128 v[116:119], v86 offset:34816
	ds_read_b128 v[120:123], v86 offset:35840
	ds_read_b128 v[124:127], v86 offset:36864
	ds_read_b128 v[128:131], v86 offset:37888
	ds_read_b128 v[132:135], v86 offset:38912
	ds_read_b128 v[136:139], v86 offset:39936
	global_load_lds_dwordx4 v66, s[54:55]
	s_mov_b32 m0, s88
	s_nop 0
	global_load_lds_dwordx4 v76, s[54:55]
	s_waitcnt vmcnt(8)
	s_waitcnt lgkmcnt(0)
	s_setprio 1
	s_barrier
	v_mfma_f32_16x16x32_bf16 v[62:65], v[88:91], v[108:111], v[62:65]
	v_mfma_f32_16x16x32_bf16 v[62:65], v[92:95], v[112:115], v[62:65]
	v_mfma_f32_16x16x32_bf16 v[54:57], v[92:95], v[120:123], v[54:57]
	v_mfma_f32_16x16x32_bf16 v[54:57], v[88:91], v[116:119], v[54:57]
	v_mfma_f32_16x16x32_bf16 v[46:49], v[88:91], v[124:127], v[46:49]
	v_mfma_f32_16x16x32_bf16 v[46:49], v[92:95], v[128:131], v[46:49]
	v_mfma_f32_16x16x32_bf16 v[38:41], v[92:95], v[136:139], v[38:41]
	v_mfma_f32_16x16x32_bf16 v[38:41], v[88:91], v[132:135], v[38:41]
	v_mfma_f32_16x16x32_bf16 v[34:37], v[100:103], v[132:135], v[34:37]
	v_mfma_f32_16x16x32_bf16 v[34:37], v[104:107], v[136:139], v[34:37]
	v_mfma_f32_16x16x32_bf16 v[58:61], v[104:107], v[112:115], v[58:61]
	v_mfma_f32_16x16x32_bf16 v[58:61], v[100:103], v[108:111], v[58:61]
	v_mfma_f32_16x16x32_bf16 v[50:53], v[100:103], v[116:119], v[50:53]
	v_mfma_f32_16x16x32_bf16 v[50:53], v[104:107], v[120:123], v[50:53]
	v_mfma_f32_16x16x32_bf16 v[42:45], v[104:107], v[128:131], v[42:45]
	v_mfma_f32_16x16x32_bf16 v[42:45], v[100:103], v[124:127], v[42:45]
	s_setprio 0
	s_setprio 1
	s_setprio 0
	s_barrier
	s_add_i32 s54, s95, s29
	s_add_u32 s98, s52, s14
	s_addc_u32 s99, s53, s15
	s_mov_b32 m0, s54
	ds_read_b128 v[108:111], v86 offset:49152
	ds_read_b128 v[112:115], v86 offset:50176
	ds_read_b128 v[116:119], v86 offset:51200
	ds_read_b128 v[120:123], v86 offset:52224
	ds_read_b128 v[124:127], v86 offset:53248
	ds_read_b128 v[128:131], v86 offset:54272
	ds_read_b128 v[132:135], v86 offset:55296
	ds_read_b128 v[136:139], v86 offset:56320
	global_load_lds_dwordx4 v78, s[98:99]
	s_add_i32 m0, s54, 0x2000
	s_add_u32 s52, s52, 0x100080
	s_addc_u32 s53, s53, 0
	global_load_lds_dwordx4 v74, s[98:99]
	s_mov_b32 m0, s92
	s_nop 0
	global_load_lds_dwordx4 v78, s[52:53]
	s_mov_b32 m0, s93
	s_nop 0
	global_load_lds_dwordx4 v74, s[52:53]
	v_lshl_add_u64 v[96:97], v[142:143], 0, s[14:15]
	s_mov_b32 m0, s90
	s_nop 0
	global_load_lds_dwordx4 v[96:97], off
	v_lshl_add_u64 v[96:97], v[144:145], 0, s[14:15]
	s_mov_b32 m0, s91
	s_nop 0
	global_load_lds_dwordx4 v[96:97], off
	s_waitcnt vmcnt(8)
	s_waitcnt lgkmcnt(0)
	s_setprio 1
	s_barrier
	v_mfma_f32_16x16x32_bf16 v[30:33], v[88:91], v[108:111], v[30:33]
	v_mfma_f32_16x16x32_bf16 v[30:33], v[92:95], v[112:115], v[30:33]
	v_mfma_f32_16x16x32_bf16 v[22:25], v[92:95], v[120:123], v[22:25]
	v_mfma_f32_16x16x32_bf16 v[22:25], v[88:91], v[116:119], v[22:25]
	v_mfma_f32_16x16x32_bf16 v[14:17], v[88:91], v[124:127], v[14:17]
	v_mfma_f32_16x16x32_bf16 v[14:17], v[92:95], v[128:131], v[14:17]
	v_mfma_f32_16x16x32_bf16 v[6:9], v[92:95], v[136:139], v[6:9]
	v_mfma_f32_16x16x32_bf16 v[6:9], v[88:91], v[132:135], v[6:9]
	v_mfma_f32_16x16x32_bf16 v[2:5], v[100:103], v[132:135], v[2:5]
	v_mfma_f32_16x16x32_bf16 v[2:5], v[104:107], v[136:139], v[2:5]
	v_mfma_f32_16x16x32_bf16 v[26:29], v[104:107], v[112:115], v[26:29]
	v_mfma_f32_16x16x32_bf16 v[26:29], v[100:103], v[108:111], v[26:29]
	v_mfma_f32_16x16x32_bf16 v[18:21], v[100:103], v[116:119], v[18:21]
	v_mfma_f32_16x16x32_bf16 v[18:21], v[104:107], v[120:123], v[18:21]
	v_mfma_f32_16x16x32_bf16 v[10:13], v[104:107], v[128:131], v[10:13]
	v_mfma_f32_16x16x32_bf16 v[10:13], v[100:103], v[124:127], v[10:13]
	s_setprio 0
	s_setprio 1
	s_setprio 0
	s_barrier
	s_cmp_ge_u32 s10, s28
	s_mov_b32 s52, s10
	s_cbranch_scc0 .LBB0_592
	s_cmpk_lt_u32 s26, 0x100
	s_cbranch_scc0 .LBB0_482
	s_barrier
	s_branch .LBB0_482

; #define PG8_STAGE(bufoff, gbase, voff) do { _Pragma("unroll") for (int _i = 0; _i < 2; ++_i) \
;         __builtin_amdgcn_global_load_lds((const unsigned*)((const char*)(gbase) + (voff)[_i]), (PG8_LAS unsigned*)(lds + (bufoff) + ldsw + _i * 8192), 16, 0, 0); } while (0)
; #define PG8_LDA(dst, b, h) do { _Pragma("unroll") for (int m = 0; m < 4; ++m) _Pragma("unroll") for (int k = 0; k < 2; ++k) dst[m][k] = *(const PG8_LAS bf16x8*)(lds + PG8_SA(b, h) + aoff + m * 2048 + k * 1024); } while (0)
; #define PG8_LDB(dst, b, h) do { _Pragma("unroll") for (int n = 0; n < 2; ++n) _Pragma("unroll") for (int k = 0; k < 2; ++k) dst[n][k] = *(const PG8_LAS bf16x8*)(lds + PG8_SB(b, h) + boff + n * 2048 + k * 1024); } while (0)
; #define PG8_MMA(ai, bj, At, Bt) do { __builtin_amdgcn_s_setprio(1); _Pragma("unroll") for (int m = 0; m < 4; ++m) _Pragma("unroll") for (int n = 0; n < 2; ++n) _Pragma("unroll") for (int k = 0; k < 2; ++k) \
;         acc[ai][bj][m][n] = __builtin_amdgcn_mfma_f32_16x16x32_bf16(Bt[n][k], At[m][k], acc[ai][bj][m][n], 0, 0, 0); __builtin_amdgcn_s_setprio(0); } while (0)
; #define PG8_WAIT_V(n) asm volatile("s_waitcnt vmcnt(" #n ")" ::: "memory")
; #define PG8_WAIT_L(n) asm volatile("s_waitcnt lgkmcnt(" #n ")" ::: "memory")
; template <class Epi, class Sched, bool ALIGN_EPI = false, bool SP2 = false>
; __device__ __forceinline__ void gemm_phase(PG8_LAS unsigned char* lds, const Gemm g, const Sched& S, const Epi& E) {
;     ...
;             const bool last = (t == nt - 2);
;             const char* a1 = cA + (size_t)(t + 1) * kstep;
;             const char* a2 = last ? nA : cA + (size_t)(t + 2) * kstep; const char* b2 = last ? nB : cB + (size_t)(t + 2) * kstep;
;             const char* a3 = a2 + kstep; const char* b3 = b2 + kstep;
;             if (last && has_next) S.a_ready(nxt);
;             if constexpr (SP2) {
;             PG8_LDB(B0, 0, 0); PG8_LDB(B1, 0, 1); PG8_SCHED; PG8_LDA(At, 0, 0); PG8_STAGE(PG8_SA(1, 1), a1 + hstep, voffA);
;             PG8_WAIT_V(8); PG8_WAIT_L(0); PG8_BAR; PG8_MMA(0, 0, At, B0); PG8_MMA(0, 1, At, B1); PG8_BAR; PG8_SCHED;
;             PG8_LDA(At, 0, 1); PG8_STAGE(PG8_SB(0, 0), b2, voffB); PG8_STAGE(PG8_SB(0, 1), b2 + hstep, voffB); PG8_STAGE(PG8_SA(0, 0), a2, voffA);
;             PG8_WAIT_V(8); PG8_WAIT_L(0); PG8_BAR; PG8_MMA(1, 0, At, B0); PG8_MMA(1, 1, At, B1); PG8_BAR; PG8_SCHED;
.LBB0_1062:
	ds_read_b128 v[146:149], v155
	ds_read_b128 v[158:161], v155 offset:1024
	ds_read_b128 v[168:171], v155 offset:2048
	ds_read_b128 v[172:175], v155 offset:3072
	ds_read_b128 v[176:179], v156
	ds_read_b128 v[180:183], v156 offset:1024
	ds_read_b128 v[184:187], v156 offset:2048
	ds_read_b128 v[188:191], v156 offset:3072
	s_add_u32 s72, s70, 0xfff80080
	s_addc_u32 s73, s71, -1
	s_cmp_eq_u32 s77, 28
	s_cselect_b32 s75, s34, s73
	s_cselect_b32 s74, s35, s72
	s_cselect_b32 s73, s61, s76
	s_cselect_b32 s72, s63, s69
	s_add_i32 m0, s25, 0xc000
	ds_read_b128 v[200:203], v157
	ds_read_b128 v[204:207], v157 offset:1024
	ds_read_b128 v[208:211], v157 offset:2048
	ds_read_b128 v[212:215], v157 offset:3072
	ds_read_b128 v[216:219], v157 offset:4096
	ds_read_b128 v[220:223], v157 offset:5120
	ds_read_b128 v[224:227], v157 offset:6144
	ds_read_b128 v[228:231], v157 offset:7168
	global_load_lds_dwordx4 v138, s[70:71]
	s_add_i32 m0, s25, 0xe000
	s_nop 0
	global_load_lds_dwordx4 v140, s[70:71]
	s_waitcnt vmcnt(8)
	s_waitcnt lgkmcnt(0)
	s_setprio 1
	s_barrier
	v_mfma_f32_16x16x32_bf16 v[126:129], v[146:149], v[200:203], v[126:129]
	v_mfma_f32_16x16x32_bf16 v[126:129], v[158:161], v[204:207], v[126:129]
	v_mfma_f32_16x16x32_bf16 v[110:113], v[158:161], v[212:215], v[110:113]
	v_mfma_f32_16x16x32_bf16 v[110:113], v[146:149], v[208:211], v[110:113]
	v_mfma_f32_16x16x32_bf16 v[94:97], v[146:149], v[216:219], v[94:97]
	v_mfma_f32_16x16x32_bf16 v[94:97], v[158:161], v[220:223], v[94:97]
	v_mfma_f32_16x16x32_bf16 v[78:81], v[158:161], v[228:231], v[78:81]
	v_mfma_f32_16x16x32_bf16 v[78:81], v[146:149], v[224:227], v[78:81]
	v_mfma_f32_16x16x32_bf16 v[74:77], v[168:171], v[224:227], v[74:77]
	v_mfma_f32_16x16x32_bf16 v[74:77], v[172:175], v[228:231], v[74:77]
	v_mfma_f32_16x16x32_bf16 v[122:125], v[172:175], v[204:207], v[122:125]
	v_mfma_f32_16x16x32_bf16 v[122:125], v[168:171], v[200:203], v[122:125]
	v_mfma_f32_16x16x32_bf16 v[106:109], v[168:171], v[208:211], v[106:109]
	v_mfma_f32_16x16x32_bf16 v[106:109], v[172:175], v[212:215], v[106:109]
	v_mfma_f32_16x16x32_bf16 v[90:93], v[172:175], v[220:223], v[90:93]
	v_mfma_f32_16x16x32_bf16 v[90:93], v[168:171], v[216:219], v[90:93]
	s_setprio 0
	s_setprio 1
	v_mfma_f32_16x16x32_bf16 v[86:89], v[176:179], v[216:219], v[86:89]
	v_mfma_f32_16x16x32_bf16 v[86:89], v[180:183], v[220:223], v[86:89]
	v_mfma_f32_16x16x32_bf16 v[118:121], v[180:183], v[204:207], v[118:121]
	v_mfma_f32_16x16x32_bf16 v[118:121], v[176:179], v[200:203], v[118:121]
	v_mfma_f32_16x16x32_bf16 v[102:105], v[176:179], v[208:211], v[102:105]
	v_mfma_f32_16x16x32_bf16 v[102:105], v[180:183], v[212:215], v[102:105]
	v_mfma_f32_16x16x32_bf16 v[70:73], v[180:183], v[228:231], v[70:73]
	v_mfma_f32_16x16x32_bf16 v[70:73], v[176:179], v[224:227], v[70:73]
	v_mfma_f32_16x16x32_bf16 v[66:69], v[184:187], v[224:227], v[66:69]
	v_mfma_f32_16x16x32_bf16 v[66:69], v[188:191], v[228:231], v[66:69]
	v_mfma_f32_16x16x32_bf16 v[114:117], v[188:191], v[204:207], v[114:117]
	v_mfma_f32_16x16x32_bf16 v[114:117], v[184:187], v[200:203], v[114:117]
	v_mfma_f32_16x16x32_bf16 v[98:101], v[184:187], v[208:211], v[98:101]
	v_mfma_f32_16x16x32_bf16 v[98:101], v[188:191], v[212:215], v[98:101]
	v_mfma_f32_16x16x32_bf16 v[82:85], v[188:191], v[220:223], v[82:85]
	v_mfma_f32_16x16x32_bf16 v[82:85], v[184:187], v[216:219], v[82:85]
	s_barrier
	s_setprio 0
	s_add_i32 s78, s31, s2
	s_mov_b32 m0, s78
	ds_read_b128 v[200:203], v157 offset:16384
	ds_read_b128 v[204:207], v157 offset:17408
	ds_read_b128 v[208:211], v157 offset:18432
	ds_read_b128 v[212:215], v157 offset:19456
	ds_read_b128 v[216:219], v157 offset:20480
	ds_read_b128 v[220:223], v157 offset:21504
	ds_read_b128 v[224:227], v157 offset:22528
	ds_read_b128 v[228:231], v157 offset:23552
	global_load_lds_dwordx4 v134, s[72:73]
	s_add_i32 m0, s78, 0x2000
	s_add_u32 s78, s72, 0x80000
	s_addc_u32 s79, s73, 0
	s_add_i32 s80, s40, s2
	global_load_lds_dwordx4 v130, s[72:73]
	s_mov_b32 m0, s80
	v_lshl_add_u64 v[232:233], s[74:75], 0, v[132:133]
	global_load_lds_dwordx4 v134, s[78:79]
	s_add_i32 m0, s80, 0x2000
	s_nop 0
	global_load_lds_dwordx4 v130, s[78:79]
	v_lshl_add_u64 v[192:193], s[74:75], 0, v[136:137]
	s_mov_b32 m0, s25
	s_nop 0
	global_load_lds_dwordx4 v136, s[74:75]
	s_mov_b32 m0, s26
	s_nop 0
	global_load_lds_dwordx4 v132, s[74:75]
	s_waitcnt vmcnt(8)
	s_waitcnt lgkmcnt(0)
	s_setprio 1
	s_barrier
	v_mfma_f32_16x16x32_bf16 v[62:65], v[146:149], v[200:203], v[62:65]
	v_mfma_f32_16x16x32_bf16 v[62:65], v[158:161], v[204:207], v[62:65]
	v_mfma_f32_16x16x32_bf16 v[46:49], v[158:161], v[212:215], v[46:49]
	v_mfma_f32_16x16x32_bf16 v[46:49], v[146:149], v[208:211], v[46:49]
	v_mfma_f32_16x16x32_bf16 v[30:33], v[146:149], v[216:219], v[30:33]
	v_mfma_f32_16x16x32_bf16 v[30:33], v[158:161], v[220:223], v[30:33]
	v_mfma_f32_16x16x32_bf16 v[14:17], v[158:161], v[228:231], v[14:17]
	v_mfma_f32_16x16x32_bf16 v[14:17], v[146:149], v[224:227], v[14:17]
	v_mfma_f32_16x16x32_bf16 v[10:13], v[168:171], v[224:227], v[10:13]
	v_mfma_f32_16x16x32_bf16 v[10:13], v[172:175], v[228:231], v[10:13]
	v_mfma_f32_16x16x32_bf16 v[58:61], v[172:175], v[204:207], v[58:61]
	v_mfma_f32_16x16x32_bf16 v[58:61], v[168:171], v[200:203], v[58:61]
	v_mfma_f32_16x16x32_bf16 v[42:45], v[168:171], v[208:211], v[42:45]
	v_mfma_f32_16x16x32_bf16 v[42:45], v[172:175], v[212:215], v[42:45]
	v_mfma_f32_16x16x32_bf16 v[26:29], v[172:175], v[220:223], v[26:29]
	v_mfma_f32_16x16x32_bf16 v[26:29], v[168:171], v[216:219], v[26:29]
	s_setprio 0
	s_setprio 1
	v_mfma_f32_16x16x32_bf16 v[22:25], v[176:179], v[216:219], v[22:25]
	v_mfma_f32_16x16x32_bf16 v[22:25], v[180:183], v[220:223], v[22:25]
	v_mfma_f32_16x16x32_bf16 v[54:57], v[180:183], v[204:207], v[54:57]
	v_mfma_f32_16x16x32_bf16 v[54:57], v[176:179], v[200:203], v[54:57]
	v_mfma_f32_16x16x32_bf16 v[38:41], v[176:179], v[208:211], v[38:41]
	v_mfma_f32_16x16x32_bf16 v[38:41], v[180:183], v[212:215], v[38:41]
	v_mfma_f32_16x16x32_bf16 v[6:9], v[180:183], v[228:231], v[6:9]
	v_mfma_f32_16x16x32_bf16 v[6:9], v[176:179], v[224:227], v[6:9]
	v_mfma_f32_16x16x32_bf16 v[2:5], v[184:187], v[224:227], v[2:5]
	v_mfma_f32_16x16x32_bf16 v[2:5], v[188:191], v[228:231], v[2:5]
	v_mfma_f32_16x16x32_bf16 v[50:53], v[188:191], v[204:207], v[50:53]
	v_mfma_f32_16x16x32_bf16 v[50:53], v[184:187], v[200:203], v[50:53]
	v_mfma_f32_16x16x32_bf16 v[34:37], v[184:187], v[208:211], v[34:37]
	v_mfma_f32_16x16x32_bf16 v[34:37], v[188:191], v[212:215], v[34:37]
	v_mfma_f32_16x16x32_bf16 v[18:21], v[188:191], v[220:223], v[18:21]
	v_mfma_f32_16x16x32_bf16 v[18:21], v[184:187], v[216:219], v[18:21]
	s_barrier
; #define PG8_STAGE(bufoff, gbase, voff) do { _Pragma("unroll") for (int _i = 0; _i < 2; ++_i) \
;         __builtin_amdgcn_global_load_lds((const unsigned*)((const char*)(gbase) + (voff)[_i]), (PG8_LAS unsigned*)(lds + (bufoff) + ldsw + _i * 8192), 16, 0, 0); } while (0)
; #define PG8_LDA(dst, b, h) do { _Pragma("unroll") for (int m = 0; m < 4; ++m) _Pragma("unroll") for (int k = 0; k < 2; ++k) dst[m][k] = *(const PG8_LAS bf16x8*)(lds + PG8_SA(b, h) + aoff + m * 2048 + k * 1024); } while (0)
; #define PG8_LDB(dst, b, h) do { _Pragma("unroll") for (int n = 0; n < 2; ++n) _Pragma("unroll") for (int k = 0; k < 2; ++k) dst[n][k] = *(const PG8_LAS bf16x8*)(lds + PG8_SB(b, h) + boff + n * 2048 + k * 1024); } while (0)
; #define PG8_MMA(ai, bj, At, Bt) do { __builtin_amdgcn_s_setprio(1); _Pragma("unroll") for (int m = 0; m < 4; ++m) _Pragma("unroll") for (int n = 0; n < 2; ++n) _Pragma("unroll") for (int k = 0; k < 2; ++k) \
;         acc[ai][bj][m][n] = __builtin_amdgcn_mfma_f32_16x16x32_bf16(Bt[n][k], At[m][k], acc[ai][bj][m][n], 0, 0, 0); __builtin_amdgcn_s_setprio(0); } while (0)
; #define PG8_WAIT_V(n) asm volatile("s_waitcnt vmcnt(" #n ")" ::: "memory")
; #define PG8_WAIT_L(n) asm volatile("s_waitcnt lgkmcnt(" #n ")" ::: "memory")
; #define PG8_BAR __builtin_amdgcn_s_barrier()
; #define PG8_SCHED __builtin_amdgcn_sched_barrier(0)
; template <class Epi, class Sched, bool ALIGN_EPI = false, bool SP2 = false>
; __device__ __forceinline__ void gemm_phase(PG8_LAS unsigned char* lds, const Gemm g, const Sched& S, const Epi& E) {
;     ...
;             PG8_LDB(B0, 1, 0); PG8_LDB(B1, 1, 1); PG8_SCHED; PG8_LDA(At, 1, 0); PG8_STAGE(PG8_SA(0, 1), a2 + hstep, voffA);
;             PG8_WAIT_V(8); PG8_WAIT_L(0); PG8_BAR; PG8_MMA(0, 0, At, B0); PG8_MMA(0, 1, At, B1); PG8_BAR; PG8_SCHED;
;             PG8_LDA(At, 1, 1); PG8_STAGE(PG8_SB(1, 0), b3, voffB); PG8_STAGE(PG8_SB(1, 1), b3 + hstep, voffB); PG8_STAGE(PG8_SA(1, 0), a3, voffA);
;             PG8_WAIT_V(8); PG8_WAIT_L(0); PG8_BAR; PG8_MMA(1, 0, At, B0); PG8_MMA(1, 1, At, B1); PG8_BAR; PG8_SCHED;
	s_setprio 0
	s_add_i32 s78, 0, 0x18000
	v_add_u32_e32 v166, s78, v153
	s_add_i32 s79, 0, 0x1c000
	ds_read_b128 v[146:149], v166
	ds_read_b128 v[158:161], v166 offset:1024
	ds_read_b128 v[168:171], v166 offset:2048
	ds_read_b128 v[172:175], v166 offset:3072
	v_add_u32_e32 v166, s79, v153
	ds_read_b128 v[176:179], v166
	ds_read_b128 v[180:183], v166 offset:1024
	ds_read_b128 v[184:187], v166 offset:2048
	ds_read_b128 v[188:191], v166 offset:3072
	s_add_u32 s74, s74, 0x80000
	s_addc_u32 s75, s75, 0
	s_mov_b32 m0, s27
	ds_read_b128 v[200:203], v157 offset:32768
	ds_read_b128 v[204:207], v157 offset:33792
	ds_read_b128 v[208:211], v157 offset:34816
	ds_read_b128 v[212:215], v157 offset:35840
	ds_read_b128 v[216:219], v157 offset:36864
	ds_read_b128 v[220:223], v157 offset:37888
	ds_read_b128 v[224:227], v157 offset:38912
	ds_read_b128 v[228:231], v157 offset:39936
	global_load_lds_dwordx4 v136, s[74:75]
	s_mov_b32 m0, s28
	s_nop 0
	global_load_lds_dwordx4 v132, s[74:75]
	s_waitcnt vmcnt(8)
	s_waitcnt lgkmcnt(0)
	s_setprio 1
	s_barrier
	v_mfma_f32_16x16x32_bf16 v[126:129], v[146:149], v[200:203], v[126:129]
	v_mfma_f32_16x16x32_bf16 v[126:129], v[158:161], v[204:207], v[126:129]
	v_mfma_f32_16x16x32_bf16 v[110:113], v[158:161], v[212:215], v[110:113]
	v_mfma_f32_16x16x32_bf16 v[110:113], v[146:149], v[208:211], v[110:113]
	v_mfma_f32_16x16x32_bf16 v[94:97], v[146:149], v[216:219], v[94:97]
	v_mfma_f32_16x16x32_bf16 v[94:97], v[158:161], v[220:223], v[94:97]
	v_mfma_f32_16x16x32_bf16 v[78:81], v[158:161], v[228:231], v[78:81]
	v_mfma_f32_16x16x32_bf16 v[78:81], v[146:149], v[224:227], v[78:81]
	v_mfma_f32_16x16x32_bf16 v[74:77], v[168:171], v[224:227], v[74:77]
	v_mfma_f32_16x16x32_bf16 v[74:77], v[172:175], v[228:231], v[74:77]
	v_mfma_f32_16x16x32_bf16 v[122:125], v[172:175], v[204:207], v[122:125]
	v_mfma_f32_16x16x32_bf16 v[122:125], v[168:171], v[200:203], v[122:125]
	v_mfma_f32_16x16x32_bf16 v[106:109], v[168:171], v[208:211], v[106:109]
	v_mfma_f32_16x16x32_bf16 v[106:109], v[172:175], v[212:215], v[106:109]
	v_mfma_f32_16x16x32_bf16 v[90:93], v[172:175], v[220:223], v[90:93]
	v_mfma_f32_16x16x32_bf16 v[90:93], v[168:171], v[216:219], v[90:93]
	s_setprio 0
	s_setprio 1
	v_mfma_f32_16x16x32_bf16 v[86:89], v[176:179], v[216:219], v[86:89]
	v_mfma_f32_16x16x32_bf16 v[86:89], v[180:183], v[220:223], v[86:89]
	v_mfma_f32_16x16x32_bf16 v[118:121], v[180:183], v[204:207], v[118:121]
	v_mfma_f32_16x16x32_bf16 v[118:121], v[176:179], v[200:203], v[118:121]
	v_mfma_f32_16x16x32_bf16 v[102:105], v[176:179], v[208:211], v[102:105]
	v_mfma_f32_16x16x32_bf16 v[102:105], v[180:183], v[212:215], v[102:105]
	v_mfma_f32_16x16x32_bf16 v[70:73], v[180:183], v[228:231], v[70:73]
	v_mfma_f32_16x16x32_bf16 v[70:73], v[176:179], v[224:227], v[70:73]
	v_mfma_f32_16x16x32_bf16 v[66:69], v[184:187], v[224:227], v[66:69]
	v_mfma_f32_16x16x32_bf16 v[66:69], v[188:191], v[228:231], v[66:69]
	v_mfma_f32_16x16x32_bf16 v[114:117], v[188:191], v[204:207], v[114:117]
	v_mfma_f32_16x16x32_bf16 v[114:117], v[184:187], v[200:203], v[114:117]
	v_mfma_f32_16x16x32_bf16 v[98:101], v[184:187], v[208:211], v[98:101]
	v_mfma_f32_16x16x32_bf16 v[98:101], v[188:191], v[212:215], v[98:101]
	v_mfma_f32_16x16x32_bf16 v[82:85], v[188:191], v[220:223], v[82:85]
	v_mfma_f32_16x16x32_bf16 v[82:85], v[184:187], v[216:219], v[82:85]
	s_barrier
	s_setprio 0
	s_add_i32 s74, s78, s2
	s_add_u32 s98, s72, s10
	s_addc_u32 s99, s73, s11
	s_mov_b32 m0, s74
	ds_read_b128 v[200:203], v157 offset:49152
	ds_read_b128 v[204:207], v157 offset:50176
	ds_read_b128 v[208:211], v157 offset:51200
	ds_read_b128 v[212:215], v157 offset:52224
	ds_read_b128 v[216:219], v157 offset:53248
	ds_read_b128 v[220:223], v157 offset:54272
	ds_read_b128 v[224:227], v157 offset:55296
	ds_read_b128 v[228:231], v157 offset:56320
	global_load_lds_dwordx4 v134, s[98:99]
	s_add_i32 m0, s74, 0x2000
	s_add_u32 s72, s72, 0x80080
	s_addc_u32 s73, s73, 0
	s_add_i32 s74, s79, s2
	global_load_lds_dwordx4 v130, s[98:99]
	s_mov_b32 m0, s74
	s_nop 0
	global_load_lds_dwordx4 v134, s[72:73]
	s_add_i32 m0, s74, 0x2000
	s_nop 0
	global_load_lds_dwordx4 v130, s[72:73]
	v_lshl_add_u64 v[150:151], v[192:193], 0, s[10:11]
	s_mov_b32 m0, s30
	s_nop 0
	global_load_lds_dwordx4 v[150:151], off
	v_lshl_add_u64 v[150:151], v[232:233], 0, s[10:11]
	s_mov_b32 m0, s33
	s_nop 0
	global_load_lds_dwordx4 v[150:151], off
	s_waitcnt vmcnt(8)
	s_waitcnt lgkmcnt(0)
	s_setprio 1
	s_barrier
	v_mfma_f32_16x16x32_bf16 v[62:65], v[146:149], v[200:203], v[62:65]
	v_mfma_f32_16x16x32_bf16 v[62:65], v[158:161], v[204:207], v[62:65]
	v_mfma_f32_16x16x32_bf16 v[46:49], v[158:161], v[212:215], v[46:49]
	v_mfma_f32_16x16x32_bf16 v[46:49], v[146:149], v[208:211], v[46:49]
	v_mfma_f32_16x16x32_bf16 v[30:33], v[146:149], v[216:219], v[30:33]
	v_mfma_f32_16x16x32_bf16 v[30:33], v[158:161], v[220:223], v[30:33]
	v_mfma_f32_16x16x32_bf16 v[14:17], v[158:161], v[228:231], v[14:17]
	v_mfma_f32_16x16x32_bf16 v[14:17], v[146:149], v[224:227], v[14:17]
	v_mfma_f32_16x16x32_bf16 v[10:13], v[168:171], v[224:227], v[10:13]
	v_mfma_f32_16x16x32_bf16 v[10:13], v[172:175], v[228:231], v[10:13]
	v_mfma_f32_16x16x32_bf16 v[58:61], v[172:175], v[204:207], v[58:61]
	v_mfma_f32_16x16x32_bf16 v[58:61], v[168:171], v[200:203], v[58:61]
	v_mfma_f32_16x16x32_bf16 v[42:45], v[168:171], v[208:211], v[42:45]
	v_mfma_f32_16x16x32_bf16 v[42:45], v[172:175], v[212:215], v[42:45]
	v_mfma_f32_16x16x32_bf16 v[26:29], v[172:175], v[220:223], v[26:29]
	v_mfma_f32_16x16x32_bf16 v[26:29], v[168:171], v[216:219], v[26:29]
	s_setprio 0
	s_setprio 1
	v_mfma_f32_16x16x32_bf16 v[22:25], v[176:179], v[216:219], v[22:25]
	v_mfma_f32_16x16x32_bf16 v[22:25], v[180:183], v[220:223], v[22:25]
	v_mfma_f32_16x16x32_bf16 v[54:57], v[180:183], v[204:207], v[54:57]
	v_mfma_f32_16x16x32_bf16 v[54:57], v[176:179], v[200:203], v[54:57]
	v_mfma_f32_16x16x32_bf16 v[38:41], v[176:179], v[208:211], v[38:41]
	v_mfma_f32_16x16x32_bf16 v[38:41], v[180:183], v[212:215], v[38:41]
	v_mfma_f32_16x16x32_bf16 v[6:9], v[180:183], v[228:231], v[6:9]
	v_mfma_f32_16x16x32_bf16 v[6:9], v[176:179], v[224:227], v[6:9]
	v_mfma_f32_16x16x32_bf16 v[2:5], v[184:187], v[224:227], v[2:5]
	v_mfma_f32_16x16x32_bf16 v[2:5], v[188:191], v[228:231], v[2:5]
	v_mfma_f32_16x16x32_bf16 v[50:53], v[188:191], v[204:207], v[50:53]
	v_mfma_f32_16x16x32_bf16 v[50:53], v[184:187], v[200:203], v[50:53]
	v_mfma_f32_16x16x32_bf16 v[34:37], v[184:187], v[208:211], v[34:37]
	v_mfma_f32_16x16x32_bf16 v[34:37], v[188:191], v[212:215], v[34:37]
	v_mfma_f32_16x16x32_bf16 v[18:21], v[188:191], v[220:223], v[18:21]
	v_mfma_f32_16x16x32_bf16 v[18:21], v[184:187], v[216:219], v[18:21]
	s_barrier
	s_setprio 0
	s_add_i32 s77, s77, 2
	s_add_u32 s70, s70, 0x100
	s_addc_u32 s71, s71, 0
	s_add_u32 s69, s69, 0x100
	s_addc_u32 s76, s76, 0
	s_cmp_gt_u32 s77, 29
	s_cbranch_scc0 .LBB0_1062
	s_and_b64 vcc, exec, s[48:49]
	s_cbranch_vccz .LBB0_1065
	s_barrier

; #define PG8_STAGE(bufoff, gbase, voff) do { _Pragma("unroll") for (int _i = 0; _i < 2; ++_i) \
;         __builtin_amdgcn_global_load_lds((const unsigned*)((const char*)(gbase) + (voff)[_i]), (PG8_LAS unsigned*)(lds + (bufoff) + ldsw + _i * 8192), 16, 0, 0); } while (0)
; #define PG8_LDA(dst, b, h) do { _Pragma("unroll") for (int m = 0; m < 4; ++m) _Pragma("unroll") for (int k = 0; k < 2; ++k) dst[m][k] = *(const PG8_LAS bf16x8*)(lds + PG8_SA(b, h) + aoff + m * 2048 + k * 1024); } while (0)
; #define PG8_LDB(dst, b, h) do { _Pragma("unroll") for (int n = 0; n < 2; ++n) _Pragma("unroll") for (int k = 0; k < 2; ++k) dst[n][k] = *(const PG8_LAS bf16x8*)(lds + PG8_SB(b, h) + boff + n * 2048 + k * 1024); } while (0)
; #define PG8_MMA(ai, bj, At, Bt) do { __builtin_amdgcn_s_setprio(1); _Pragma("unroll") for (int m = 0; m < 4; ++m) _Pragma("unroll") for (int n = 0; n < 2; ++n) _Pragma("unroll") for (int k = 0; k < 2; ++k) \
;         acc[ai][bj][m][n] = __builtin_amdgcn_mfma_f32_16x16x32_bf16(Bt[n][k], At[m][k], acc[ai][bj][m][n], 0, 0, 0); __builtin_amdgcn_s_setprio(0); } while (0)
; #define PG8_WAIT_V(n) asm volatile("s_waitcnt vmcnt(" #n ")" ::: "memory")
; #define PG8_WAIT_L(n) asm volatile("s_waitcnt lgkmcnt(" #n ")" ::: "memory")
; template <class Epi, class Sched, bool ALIGN_EPI = false, bool SP2 = false>
; __device__ __forceinline__ void gemm_phase(PG8_LAS unsigned char* lds, const Gemm g, const Sched& S, const Epi& E) {
;     ...
;             const bool last = (t == nt - 2);
;             const char* a1 = cA + (size_t)(t + 1) * kstep;
;             const char* a2 = last ? nA : cA + (size_t)(t + 2) * kstep; const char* b2 = last ? nB : cB + (size_t)(t + 2) * kstep;
;             const char* a3 = a2 + kstep; const char* b3 = b2 + kstep;
;             if (last && has_next) S.a_ready(nxt);
;             if constexpr (SP2) {
;             PG8_LDB(B0, 0, 0); PG8_LDB(B1, 0, 1); PG8_SCHED; PG8_LDA(At, 0, 0); PG8_STAGE(PG8_SA(1, 1), a1 + hstep, voffA);
;             PG8_WAIT_V(8); PG8_WAIT_L(0); PG8_BAR; PG8_MMA(0, 0, At, B0); PG8_MMA(0, 1, At, B1); PG8_BAR; PG8_SCHED;
;             PG8_LDA(At, 0, 1); PG8_STAGE(PG8_SB(0, 0), b2, voffB); PG8_STAGE(PG8_SB(0, 1), b2 + hstep, voffB); PG8_STAGE(PG8_SA(0, 0), a2, voffA);
;             PG8_WAIT_V(8); PG8_WAIT_L(0); PG8_BAR; PG8_MMA(1, 0, At, B0); PG8_MMA(1, 1, At, B1); PG8_BAR; PG8_SCHED;
.LBB0_1078:
	ds_read_b128 v[146:149], v155
	ds_read_b128 v[158:161], v155 offset:1024
	ds_read_b128 v[168:171], v155 offset:2048
	ds_read_b128 v[172:175], v155 offset:3072
	ds_read_b128 v[176:179], v156
	ds_read_b128 v[180:183], v156 offset:1024
	ds_read_b128 v[184:187], v156 offset:2048
	ds_read_b128 v[188:191], v156 offset:3072
	s_add_u32 s68, s66, 0xfff80080
	s_addc_u32 s69, s67, -1
	s_cmp_eq_u32 s73, 28
	s_cselect_b32 s71, s34, s69
	s_cselect_b32 s70, s35, s68
	s_cselect_b32 s69, s57, s72
	s_cselect_b32 s68, s59, s65
	s_add_i32 m0, s25, 0xc000
	ds_read_b128 v[200:203], v157
	ds_read_b128 v[204:207], v157 offset:1024
	ds_read_b128 v[208:211], v157 offset:2048
	ds_read_b128 v[212:215], v157 offset:3072
	ds_read_b128 v[216:219], v157 offset:4096
	ds_read_b128 v[220:223], v157 offset:5120
	ds_read_b128 v[224:227], v157 offset:6144
	ds_read_b128 v[228:231], v157 offset:7168
	global_load_lds_dwordx4 v138, s[66:67]
	s_add_i32 m0, s25, 0xe000
	s_nop 0
	global_load_lds_dwordx4 v140, s[66:67]
	s_waitcnt vmcnt(8)
	s_waitcnt lgkmcnt(0)
	s_setprio 1
	s_barrier
	v_mfma_f32_16x16x32_bf16 v[126:129], v[146:149], v[200:203], v[126:129]
	v_mfma_f32_16x16x32_bf16 v[126:129], v[158:161], v[204:207], v[126:129]
	v_mfma_f32_16x16x32_bf16 v[110:113], v[158:161], v[212:215], v[110:113]
	v_mfma_f32_16x16x32_bf16 v[110:113], v[146:149], v[208:211], v[110:113]
	v_mfma_f32_16x16x32_bf16 v[94:97], v[146:149], v[216:219], v[94:97]
	v_mfma_f32_16x16x32_bf16 v[94:97], v[158:161], v[220:223], v[94:97]
	v_mfma_f32_16x16x32_bf16 v[78:81], v[158:161], v[228:231], v[78:81]
	v_mfma_f32_16x16x32_bf16 v[78:81], v[146:149], v[224:227], v[78:81]
	v_mfma_f32_16x16x32_bf16 v[74:77], v[168:171], v[224:227], v[74:77]
	v_mfma_f32_16x16x32_bf16 v[74:77], v[172:175], v[228:231], v[74:77]
	v_mfma_f32_16x16x32_bf16 v[122:125], v[172:175], v[204:207], v[122:125]
	v_mfma_f32_16x16x32_bf16 v[122:125], v[168:171], v[200:203], v[122:125]
	v_mfma_f32_16x16x32_bf16 v[106:109], v[168:171], v[208:211], v[106:109]
	v_mfma_f32_16x16x32_bf16 v[106:109], v[172:175], v[212:215], v[106:109]
	v_mfma_f32_16x16x32_bf16 v[90:93], v[172:175], v[220:223], v[90:93]
	v_mfma_f32_16x16x32_bf16 v[90:93], v[168:171], v[216:219], v[90:93]
	s_setprio 0
	s_setprio 1
	v_mfma_f32_16x16x32_bf16 v[86:89], v[176:179], v[216:219], v[86:89]
	v_mfma_f32_16x16x32_bf16 v[86:89], v[180:183], v[220:223], v[86:89]
	v_mfma_f32_16x16x32_bf16 v[118:121], v[180:183], v[204:207], v[118:121]
	v_mfma_f32_16x16x32_bf16 v[118:121], v[176:179], v[200:203], v[118:121]
	v_mfma_f32_16x16x32_bf16 v[102:105], v[176:179], v[208:211], v[102:105]
	v_mfma_f32_16x16x32_bf16 v[102:105], v[180:183], v[212:215], v[102:105]
	v_mfma_f32_16x16x32_bf16 v[70:73], v[180:183], v[228:231], v[70:73]
	v_mfma_f32_16x16x32_bf16 v[70:73], v[176:179], v[224:227], v[70:73]
	v_mfma_f32_16x16x32_bf16 v[66:69], v[184:187], v[224:227], v[66:69]
	v_mfma_f32_16x16x32_bf16 v[66:69], v[188:191], v[228:231], v[66:69]
	v_mfma_f32_16x16x32_bf16 v[114:117], v[188:191], v[204:207], v[114:117]
	v_mfma_f32_16x16x32_bf16 v[114:117], v[184:187], v[200:203], v[114:117]
	v_mfma_f32_16x16x32_bf16 v[98:101], v[184:187], v[208:211], v[98:101]
	v_mfma_f32_16x16x32_bf16 v[98:101], v[188:191], v[212:215], v[98:101]
	v_mfma_f32_16x16x32_bf16 v[82:85], v[188:191], v[220:223], v[82:85]
	v_mfma_f32_16x16x32_bf16 v[82:85], v[184:187], v[216:219], v[82:85]
	s_barrier
	s_setprio 0
	s_add_i32 s74, s31, s2
	s_mov_b32 m0, s74
	ds_read_b128 v[200:203], v157 offset:16384
	ds_read_b128 v[204:207], v157 offset:17408
	ds_read_b128 v[208:211], v157 offset:18432
	ds_read_b128 v[212:215], v157 offset:19456
	ds_read_b128 v[216:219], v157 offset:20480
	ds_read_b128 v[220:223], v157 offset:21504
	ds_read_b128 v[224:227], v157 offset:22528
	ds_read_b128 v[228:231], v157 offset:23552
	global_load_lds_dwordx4 v134, s[68:69]
	s_add_i32 m0, s74, 0x2000
	s_add_u32 s74, s68, 0x80000
	s_addc_u32 s75, s69, 0
	s_add_i32 s76, s40, s2
	global_load_lds_dwordx4 v130, s[68:69]
	s_mov_b32 m0, s76
	v_lshl_add_u64 v[232:233], s[70:71], 0, v[132:133]
	global_load_lds_dwordx4 v134, s[74:75]
	s_add_i32 m0, s76, 0x2000
	s_nop 0
	global_load_lds_dwordx4 v130, s[74:75]
	v_lshl_add_u64 v[192:193], s[70:71], 0, v[136:137]
	s_mov_b32 m0, s25
	s_nop 0
	global_load_lds_dwordx4 v136, s[70:71]
	s_mov_b32 m0, s26
	s_nop 0
	global_load_lds_dwordx4 v132, s[70:71]
	s_waitcnt vmcnt(8)
	s_waitcnt lgkmcnt(0)
	s_setprio 1
	s_barrier
	v_mfma_f32_16x16x32_bf16 v[62:65], v[146:149], v[200:203], v[62:65]
	v_mfma_f32_16x16x32_bf16 v[62:65], v[158:161], v[204:207], v[62:65]
	v_mfma_f32_16x16x32_bf16 v[46:49], v[158:161], v[212:215], v[46:49]
	v_mfma_f32_16x16x32_bf16 v[46:49], v[146:149], v[208:211], v[46:49]
	v_mfma_f32_16x16x32_bf16 v[30:33], v[146:149], v[216:219], v[30:33]
	v_mfma_f32_16x16x32_bf16 v[30:33], v[158:161], v[220:223], v[30:33]
	v_mfma_f32_16x16x32_bf16 v[14:17], v[158:161], v[228:231], v[14:17]
	v_mfma_f32_16x16x32_bf16 v[14:17], v[146:149], v[224:227], v[14:17]
	v_mfma_f32_16x16x32_bf16 v[10:13], v[168:171], v[224:227], v[10:13]
	v_mfma_f32_16x16x32_bf16 v[10:13], v[172:175], v[228:231], v[10:13]
	v_mfma_f32_16x16x32_bf16 v[58:61], v[172:175], v[204:207], v[58:61]
	v_mfma_f32_16x16x32_bf16 v[58:61], v[168:171], v[200:203], v[58:61]
	v_mfma_f32_16x16x32_bf16 v[42:45], v[168:171], v[208:211], v[42:45]
	v_mfma_f32_16x16x32_bf16 v[42:45], v[172:175], v[212:215], v[42:45]
	v_mfma_f32_16x16x32_bf16 v[26:29], v[172:175], v[220:223], v[26:29]
	v_mfma_f32_16x16x32_bf16 v[26:29], v[168:171], v[216:219], v[26:29]
	s_setprio 0
	s_setprio 1
	v_mfma_f32_16x16x32_bf16 v[22:25], v[176:179], v[216:219], v[22:25]
	v_mfma_f32_16x16x32_bf16 v[22:25], v[180:183], v[220:223], v[22:25]
	v_mfma_f32_16x16x32_bf16 v[54:57], v[180:183], v[204:207], v[54:57]
	v_mfma_f32_16x16x32_bf16 v[54:57], v[176:179], v[200:203], v[54:57]
	v_mfma_f32_16x16x32_bf16 v[38:41], v[176:179], v[208:211], v[38:41]
	v_mfma_f32_16x16x32_bf16 v[38:41], v[180:183], v[212:215], v[38:41]
	v_mfma_f32_16x16x32_bf16 v[6:9], v[180:183], v[228:231], v[6:9]
	v_mfma_f32_16x16x32_bf16 v[6:9], v[176:179], v[224:227], v[6:9]
	v_mfma_f32_16x16x32_bf16 v[2:5], v[184:187], v[224:227], v[2:5]
	v_mfma_f32_16x16x32_bf16 v[2:5], v[188:191], v[228:231], v[2:5]
	v_mfma_f32_16x16x32_bf16 v[50:53], v[188:191], v[204:207], v[50:53]
	v_mfma_f32_16x16x32_bf16 v[50:53], v[184:187], v[200:203], v[50:53]
	v_mfma_f32_16x16x32_bf16 v[34:37], v[184:187], v[208:211], v[34:37]
	v_mfma_f32_16x16x32_bf16 v[34:37], v[188:191], v[212:215], v[34:37]
	v_mfma_f32_16x16x32_bf16 v[18:21], v[188:191], v[220:223], v[18:21]
	v_mfma_f32_16x16x32_bf16 v[18:21], v[184:187], v[216:219], v[18:21]
	s_barrier
; #define PG8_STAGE(bufoff, gbase, voff) do { _Pragma("unroll") for (int _i = 0; _i < 2; ++_i) \
;         __builtin_amdgcn_global_load_lds((const unsigned*)((const char*)(gbase) + (voff)[_i]), (PG8_LAS unsigned*)(lds + (bufoff) + ldsw + _i * 8192), 16, 0, 0); } while (0)
; #define PG8_LDA(dst, b, h) do { _Pragma("unroll") for (int m = 0; m < 4; ++m) _Pragma("unroll") for (int k = 0; k < 2; ++k) dst[m][k] = *(const PG8_LAS bf16x8*)(lds + PG8_SA(b, h) + aoff + m * 2048 + k * 1024); } while (0)
; #define PG8_LDB(dst, b, h) do { _Pragma("unroll") for (int n = 0; n < 2; ++n) _Pragma("unroll") for (int k = 0; k < 2; ++k) dst[n][k] = *(const PG8_LAS bf16x8*)(lds + PG8_SB(b, h) + boff + n * 2048 + k * 1024); } while (0)
; #define PG8_MMA(ai, bj, At, Bt) do { __builtin_amdgcn_s_setprio(1); _Pragma("unroll") for (int m = 0; m < 4; ++m) _Pragma("unroll") for (int n = 0; n < 2; ++n) _Pragma("unroll") for (int k = 0; k < 2; ++k) \
;         acc[ai][bj][m][n] = __builtin_amdgcn_mfma_f32_16x16x32_bf16(Bt[n][k], At[m][k], acc[ai][bj][m][n], 0, 0, 0); __builtin_amdgcn_s_setprio(0); } while (0)
; #define PG8_WAIT_V(n) asm volatile("s_waitcnt vmcnt(" #n ")" ::: "memory")
; #define PG8_WAIT_L(n) asm volatile("s_waitcnt lgkmcnt(" #n ")" ::: "memory")
; #define PG8_BAR __builtin_amdgcn_s_barrier()
; #define PG8_SCHED __builtin_amdgcn_sched_barrier(0)
; template <class Epi, class Sched, bool ALIGN_EPI = false, bool SP2 = false>
; __device__ __forceinline__ void gemm_phase(PG8_LAS unsigned char* lds, const Gemm g, const Sched& S, const Epi& E) {
;     ...
;             PG8_LDB(B0, 1, 0); PG8_LDB(B1, 1, 1); PG8_SCHED; PG8_LDA(At, 1, 0); PG8_STAGE(PG8_SA(0, 1), a2 + hstep, voffA);
;             PG8_WAIT_V(8); PG8_WAIT_L(0); PG8_BAR; PG8_MMA(0, 0, At, B0); PG8_MMA(0, 1, At, B1); PG8_BAR; PG8_SCHED;
;             PG8_LDA(At, 1, 1); PG8_STAGE(PG8_SB(1, 0), b3, voffB); PG8_STAGE(PG8_SB(1, 1), b3 + hstep, voffB); PG8_STAGE(PG8_SA(1, 0), a3, voffA);
;             PG8_WAIT_V(8); PG8_WAIT_L(0); PG8_BAR; PG8_MMA(1, 0, At, B0); PG8_MMA(1, 1, At, B1); PG8_BAR; PG8_SCHED;
	s_setprio 0
	s_add_i32 s74, 0, 0x18000
	v_add_u32_e32 v166, s74, v153
	s_add_i32 s75, 0, 0x1c000
	ds_read_b128 v[146:149], v166
	ds_read_b128 v[158:161], v166 offset:1024
	ds_read_b128 v[168:171], v166 offset:2048
	ds_read_b128 v[172:175], v166 offset:3072
	v_add_u32_e32 v166, s75, v153
	ds_read_b128 v[176:179], v166
	ds_read_b128 v[180:183], v166 offset:1024
	ds_read_b128 v[184:187], v166 offset:2048
	ds_read_b128 v[188:191], v166 offset:3072
	s_add_u32 s70, s70, 0x80000
	s_addc_u32 s71, s71, 0
	s_mov_b32 m0, s27
	ds_read_b128 v[200:203], v157 offset:32768
	ds_read_b128 v[204:207], v157 offset:33792
	ds_read_b128 v[208:211], v157 offset:34816
	ds_read_b128 v[212:215], v157 offset:35840
	ds_read_b128 v[216:219], v157 offset:36864
	ds_read_b128 v[220:223], v157 offset:37888
	ds_read_b128 v[224:227], v157 offset:38912
	ds_read_b128 v[228:231], v157 offset:39936
	global_load_lds_dwordx4 v136, s[70:71]
	s_mov_b32 m0, s28
	s_nop 0
	global_load_lds_dwordx4 v132, s[70:71]
	s_waitcnt vmcnt(8)
	s_waitcnt lgkmcnt(0)
	s_setprio 1
	s_barrier
	v_mfma_f32_16x16x32_bf16 v[126:129], v[146:149], v[200:203], v[126:129]
	v_mfma_f32_16x16x32_bf16 v[126:129], v[158:161], v[204:207], v[126:129]
	v_mfma_f32_16x16x32_bf16 v[110:113], v[158:161], v[212:215], v[110:113]
	v_mfma_f32_16x16x32_bf16 v[110:113], v[146:149], v[208:211], v[110:113]
	v_mfma_f32_16x16x32_bf16 v[94:97], v[146:149], v[216:219], v[94:97]
	v_mfma_f32_16x16x32_bf16 v[94:97], v[158:161], v[220:223], v[94:97]
	v_mfma_f32_16x16x32_bf16 v[78:81], v[158:161], v[228:231], v[78:81]
	v_mfma_f32_16x16x32_bf16 v[78:81], v[146:149], v[224:227], v[78:81]
	v_mfma_f32_16x16x32_bf16 v[74:77], v[168:171], v[224:227], v[74:77]
	v_mfma_f32_16x16x32_bf16 v[74:77], v[172:175], v[228:231], v[74:77]
	v_mfma_f32_16x16x32_bf16 v[122:125], v[172:175], v[204:207], v[122:125]
	v_mfma_f32_16x16x32_bf16 v[122:125], v[168:171], v[200:203], v[122:125]
	v_mfma_f32_16x16x32_bf16 v[106:109], v[168:171], v[208:211], v[106:109]
	v_mfma_f32_16x16x32_bf16 v[106:109], v[172:175], v[212:215], v[106:109]
	v_mfma_f32_16x16x32_bf16 v[90:93], v[172:175], v[220:223], v[90:93]
	v_mfma_f32_16x16x32_bf16 v[90:93], v[168:171], v[216:219], v[90:93]
	s_setprio 0
	s_setprio 1
	v_mfma_f32_16x16x32_bf16 v[86:89], v[176:179], v[216:219], v[86:89]
	v_mfma_f32_16x16x32_bf16 v[86:89], v[180:183], v[220:223], v[86:89]
	v_mfma_f32_16x16x32_bf16 v[118:121], v[180:183], v[204:207], v[118:121]
	v_mfma_f32_16x16x32_bf16 v[118:121], v[176:179], v[200:203], v[118:121]
	v_mfma_f32_16x16x32_bf16 v[102:105], v[176:179], v[208:211], v[102:105]
	v_mfma_f32_16x16x32_bf16 v[102:105], v[180:183], v[212:215], v[102:105]
	v_mfma_f32_16x16x32_bf16 v[70:73], v[180:183], v[228:231], v[70:73]
	v_mfma_f32_16x16x32_bf16 v[70:73], v[176:179], v[224:227], v[70:73]
	v_mfma_f32_16x16x32_bf16 v[66:69], v[184:187], v[224:227], v[66:69]
	v_mfma_f32_16x16x32_bf16 v[66:69], v[188:191], v[228:231], v[66:69]
	v_mfma_f32_16x16x32_bf16 v[114:117], v[188:191], v[204:207], v[114:117]
	v_mfma_f32_16x16x32_bf16 v[114:117], v[184:187], v[200:203], v[114:117]
	v_mfma_f32_16x16x32_bf16 v[98:101], v[184:187], v[208:211], v[98:101]
	v_mfma_f32_16x16x32_bf16 v[98:101], v[188:191], v[212:215], v[98:101]
	v_mfma_f32_16x16x32_bf16 v[82:85], v[188:191], v[220:223], v[82:85]
	v_mfma_f32_16x16x32_bf16 v[82:85], v[184:187], v[216:219], v[82:85]
	s_barrier
	s_setprio 0
	s_add_i32 s70, s74, s2
	s_add_u32 s98, s68, s8
	s_addc_u32 s99, s69, s9
	s_mov_b32 m0, s70
	ds_read_b128 v[200:203], v157 offset:49152
	ds_read_b128 v[204:207], v157 offset:50176
	ds_read_b128 v[208:211], v157 offset:51200
	ds_read_b128 v[212:215], v157 offset:52224
	ds_read_b128 v[216:219], v157 offset:53248
	ds_read_b128 v[220:223], v157 offset:54272
	ds_read_b128 v[224:227], v157 offset:55296
	ds_read_b128 v[228:231], v157 offset:56320
	global_load_lds_dwordx4 v134, s[98:99]
	s_add_i32 m0, s70, 0x2000
	s_add_u32 s68, s68, 0x80080
	s_addc_u32 s69, s69, 0
	s_add_i32 s70, s75, s2
	global_load_lds_dwordx4 v130, s[98:99]
	s_mov_b32 m0, s70
	s_nop 0
	global_load_lds_dwordx4 v134, s[68:69]
	s_add_i32 m0, s70, 0x2000
	s_nop 0
	global_load_lds_dwordx4 v130, s[68:69]
	v_lshl_add_u64 v[150:151], v[192:193], 0, s[8:9]
	s_mov_b32 m0, s30
	s_nop 0
	global_load_lds_dwordx4 v[150:151], off
	v_lshl_add_u64 v[150:151], v[232:233], 0, s[8:9]
	s_mov_b32 m0, s33
	s_nop 0
	global_load_lds_dwordx4 v[150:151], off
	s_waitcnt vmcnt(8)
	s_waitcnt lgkmcnt(0)
	s_setprio 1
	s_barrier
	v_mfma_f32_16x16x32_bf16 v[62:65], v[146:149], v[200:203], v[62:65]
	v_mfma_f32_16x16x32_bf16 v[62:65], v[158:161], v[204:207], v[62:65]
	v_mfma_f32_16x16x32_bf16 v[46:49], v[158:161], v[212:215], v[46:49]
	v_mfma_f32_16x16x32_bf16 v[46:49], v[146:149], v[208:211], v[46:49]
	v_mfma_f32_16x16x32_bf16 v[30:33], v[146:149], v[216:219], v[30:33]
	v_mfma_f32_16x16x32_bf16 v[30:33], v[158:161], v[220:223], v[30:33]
	v_mfma_f32_16x16x32_bf16 v[14:17], v[158:161], v[228:231], v[14:17]
	v_mfma_f32_16x16x32_bf16 v[14:17], v[146:149], v[224:227], v[14:17]
	v_mfma_f32_16x16x32_bf16 v[10:13], v[168:171], v[224:227], v[10:13]
	v_mfma_f32_16x16x32_bf16 v[10:13], v[172:175], v[228:231], v[10:13]
	v_mfma_f32_16x16x32_bf16 v[58:61], v[172:175], v[204:207], v[58:61]
	v_mfma_f32_16x16x32_bf16 v[58:61], v[168:171], v[200:203], v[58:61]
	v_mfma_f32_16x16x32_bf16 v[42:45], v[168:171], v[208:211], v[42:45]
	v_mfma_f32_16x16x32_bf16 v[42:45], v[172:175], v[212:215], v[42:45]
	v_mfma_f32_16x16x32_bf16 v[26:29], v[172:175], v[220:223], v[26:29]
	v_mfma_f32_16x16x32_bf16 v[26:29], v[168:171], v[216:219], v[26:29]
	s_setprio 0
	s_setprio 1
	v_mfma_f32_16x16x32_bf16 v[22:25], v[176:179], v[216:219], v[22:25]
	v_mfma_f32_16x16x32_bf16 v[22:25], v[180:183], v[220:223], v[22:25]
	v_mfma_f32_16x16x32_bf16 v[54:57], v[180:183], v[204:207], v[54:57]
	v_mfma_f32_16x16x32_bf16 v[54:57], v[176:179], v[200:203], v[54:57]
	v_mfma_f32_16x16x32_bf16 v[38:41], v[176:179], v[208:211], v[38:41]
	v_mfma_f32_16x16x32_bf16 v[38:41], v[180:183], v[212:215], v[38:41]
	v_mfma_f32_16x16x32_bf16 v[6:9], v[180:183], v[228:231], v[6:9]
	v_mfma_f32_16x16x32_bf16 v[6:9], v[176:179], v[224:227], v[6:9]
	v_mfma_f32_16x16x32_bf16 v[2:5], v[184:187], v[224:227], v[2:5]
	v_mfma_f32_16x16x32_bf16 v[2:5], v[188:191], v[228:231], v[2:5]
	v_mfma_f32_16x16x32_bf16 v[50:53], v[188:191], v[204:207], v[50:53]
	v_mfma_f32_16x16x32_bf16 v[50:53], v[184:187], v[200:203], v[50:53]
	v_mfma_f32_16x16x32_bf16 v[34:37], v[184:187], v[208:211], v[34:37]
	v_mfma_f32_16x16x32_bf16 v[34:37], v[188:191], v[212:215], v[34:37]
	v_mfma_f32_16x16x32_bf16 v[18:21], v[188:191], v[220:223], v[18:21]
	v_mfma_f32_16x16x32_bf16 v[18:21], v[184:187], v[216:219], v[18:21]
	s_barrier
	s_setprio 0
	s_add_i32 s73, s73, 2
	s_add_u32 s66, s66, 0x100
	s_addc_u32 s67, s67, 0
	s_add_u32 s65, s65, 0x100
	s_addc_u32 s72, s72, 0
	s_cmp_gt_u32 s73, 29
	s_cbranch_scc0 .LBB0_1078
	s_and_b64 vcc, exec, s[10:11]
	s_cbranch_vccz .LBB0_1081
	s_barrier

; #define PG8_STAGE(bufoff, gbase, voff) do { _Pragma("unroll") for (int _i = 0; _i < 2; ++_i) \
;         __builtin_amdgcn_global_load_lds((const unsigned*)((const char*)(gbase) + (voff)[_i]), (PG8_LAS unsigned*)(lds + (bufoff) + ldsw + _i * 8192), 16, 0, 0); } while (0)
; #define PG8_LDA(dst, b, h) do { _Pragma("unroll") for (int m = 0; m < 4; ++m) _Pragma("unroll") for (int k = 0; k < 2; ++k) dst[m][k] = *(const PG8_LAS bf16x8*)(lds + PG8_SA(b, h) + aoff + m * 2048 + k * 1024); } while (0)
; #define PG8_LDB(dst, b, h) do { _Pragma("unroll") for (int n = 0; n < 2; ++n) _Pragma("unroll") for (int k = 0; k < 2; ++k) dst[n][k] = *(const PG8_LAS bf16x8*)(lds + PG8_SB(b, h) + boff + n * 2048 + k * 1024); } while (0)
; #define PG8_MMA(ai, bj, At, Bt) do { __builtin_amdgcn_s_setprio(1); _Pragma("unroll") for (int m = 0; m < 4; ++m) _Pragma("unroll") for (int n = 0; n < 2; ++n) _Pragma("unroll") for (int k = 0; k < 2; ++k) \
;         acc[ai][bj][m][n] = __builtin_amdgcn_mfma_f32_16x16x32_bf16(Bt[n][k], At[m][k], acc[ai][bj][m][n], 0, 0, 0); __builtin_amdgcn_s_setprio(0); } while (0)
; #define PG8_WAIT_V(n) asm volatile("s_waitcnt vmcnt(" #n ")" ::: "memory")
; #define PG8_WAIT_L(n) asm volatile("s_waitcnt lgkmcnt(" #n ")" ::: "memory")
; template <class Epi, class Sched, bool ALIGN_EPI = false, bool SP2 = false>
; __device__ __forceinline__ void gemm_phase(PG8_LAS unsigned char* lds, const Gemm g, const Sched& S, const Epi& E) {
;     ...
;             const bool last = (t == nt - 2);
;             const char* a1 = cA + (size_t)(t + 1) * kstep;
;             const char* a2 = last ? nA : cA + (size_t)(t + 2) * kstep; const char* b2 = last ? nB : cB + (size_t)(t + 2) * kstep;
;             const char* a3 = a2 + kstep; const char* b3 = b2 + kstep;
;             if (last && has_next) S.a_ready(nxt);
;             if constexpr (SP2) {
;             PG8_LDB(B0, 0, 0); PG8_LDB(B1, 0, 1); PG8_SCHED; PG8_LDA(At, 0, 0); PG8_STAGE(PG8_SA(1, 1), a1 + hstep, voffA);
;             PG8_WAIT_V(8); PG8_WAIT_L(0); PG8_BAR; PG8_MMA(0, 0, At, B0); PG8_MMA(0, 1, At, B1); PG8_BAR; PG8_SCHED;
;             PG8_LDA(At, 0, 1); PG8_STAGE(PG8_SB(0, 0), b2, voffB); PG8_STAGE(PG8_SB(0, 1), b2 + hstep, voffB); PG8_STAGE(PG8_SA(0, 0), a2, voffA);
;             PG8_WAIT_V(8); PG8_WAIT_L(0); PG8_BAR; PG8_MMA(1, 0, At, B0); PG8_MMA(1, 1, At, B1); PG8_BAR; PG8_SCHED;
.LBB0_1203:
	ds_read_b128 v[146:149], v171
	ds_read_b128 v[176:179], v171 offset:1024
	ds_read_b128 v[180:183], v171 offset:2048
	ds_read_b128 v[184:187], v171 offset:3072
	ds_read_b128 v[188:191], v172
	ds_read_b128 v[200:203], v172 offset:1024
	ds_read_b128 v[204:207], v172 offset:2048
	ds_read_b128 v[208:211], v172 offset:3072
	s_add_u32 s63, s64, 0xfff00080
	s_addc_u32 s66, s65, -1
	s_cmp_eq_u32 s61, 60
	s_cselect_b32 s69, s34, s66
	s_cselect_b32 s68, s35, s63
	s_cselect_b32 s67, s40, s55
	s_cselect_b32 s66, s41, s53
	s_add_i32 m0, s4, 0xc000
	ds_read_b128 v[212:215], v173
	ds_read_b128 v[216:219], v173 offset:1024
	ds_read_b128 v[220:223], v173 offset:2048
	ds_read_b128 v[224:227], v173 offset:3072
	ds_read_b128 v[228:231], v173 offset:4096
	ds_read_b128 v[240:243], v173 offset:5120
	ds_read_b128 v[244:247], v173 offset:6144
	ds_read_b128 v[248:251], v173 offset:7168
	global_load_lds_dwordx4 v138, s[64:65]
	s_add_i32 m0, s4, 0xe000
	s_nop 0
	global_load_lds_dwordx4 v140, s[64:65]
	s_waitcnt vmcnt(8)
	s_waitcnt lgkmcnt(0)
	s_setprio 1
	s_barrier
	v_mfma_f32_16x16x32_bf16 v[126:129], v[146:149], v[212:215], v[126:129]
	v_mfma_f32_16x16x32_bf16 v[126:129], v[176:179], v[216:219], v[126:129]
	v_mfma_f32_16x16x32_bf16 v[110:113], v[176:179], v[224:227], v[110:113]
	v_mfma_f32_16x16x32_bf16 v[110:113], v[146:149], v[220:223], v[110:113]
	v_mfma_f32_16x16x32_bf16 v[94:97], v[146:149], v[228:231], v[94:97]
	v_mfma_f32_16x16x32_bf16 v[94:97], v[176:179], v[240:243], v[94:97]
	v_mfma_f32_16x16x32_bf16 v[78:81], v[176:179], v[248:251], v[78:81]
	v_mfma_f32_16x16x32_bf16 v[78:81], v[146:149], v[244:247], v[78:81]
	v_mfma_f32_16x16x32_bf16 v[74:77], v[180:183], v[244:247], v[74:77]
	v_mfma_f32_16x16x32_bf16 v[74:77], v[184:187], v[248:251], v[74:77]
	v_mfma_f32_16x16x32_bf16 v[122:125], v[184:187], v[216:219], v[122:125]
	v_mfma_f32_16x16x32_bf16 v[122:125], v[180:183], v[212:215], v[122:125]
	v_mfma_f32_16x16x32_bf16 v[106:109], v[180:183], v[220:223], v[106:109]
	v_mfma_f32_16x16x32_bf16 v[106:109], v[184:187], v[224:227], v[106:109]
	v_mfma_f32_16x16x32_bf16 v[90:93], v[184:187], v[240:243], v[90:93]
	v_mfma_f32_16x16x32_bf16 v[90:93], v[180:183], v[228:231], v[90:93]
	s_setprio 0
	s_setprio 1
	v_mfma_f32_16x16x32_bf16 v[86:89], v[188:191], v[228:231], v[86:89]
	v_mfma_f32_16x16x32_bf16 v[86:89], v[200:203], v[240:243], v[86:89]
	v_mfma_f32_16x16x32_bf16 v[118:121], v[200:203], v[216:219], v[118:121]
	v_mfma_f32_16x16x32_bf16 v[118:121], v[188:191], v[212:215], v[118:121]
	v_mfma_f32_16x16x32_bf16 v[102:105], v[188:191], v[220:223], v[102:105]
	v_mfma_f32_16x16x32_bf16 v[102:105], v[200:203], v[224:227], v[102:105]
	v_mfma_f32_16x16x32_bf16 v[70:73], v[200:203], v[248:251], v[70:73]
	v_mfma_f32_16x16x32_bf16 v[70:73], v[188:191], v[244:247], v[70:73]
	v_mfma_f32_16x16x32_bf16 v[66:69], v[204:207], v[244:247], v[66:69]
	v_mfma_f32_16x16x32_bf16 v[66:69], v[208:211], v[248:251], v[66:69]
	v_mfma_f32_16x16x32_bf16 v[114:117], v[208:211], v[216:219], v[114:117]
	v_mfma_f32_16x16x32_bf16 v[114:117], v[204:207], v[212:215], v[114:117]
	v_mfma_f32_16x16x32_bf16 v[98:101], v[204:207], v[220:223], v[98:101]
	v_mfma_f32_16x16x32_bf16 v[98:101], v[208:211], v[224:227], v[98:101]
	v_mfma_f32_16x16x32_bf16 v[82:85], v[208:211], v[240:243], v[82:85]
	v_mfma_f32_16x16x32_bf16 v[82:85], v[204:207], v[228:231], v[82:85]
	s_barrier
	s_setprio 0
	s_add_i32 s63, s31, s2
	s_mov_b32 m0, s63
	ds_read_b128 v[212:215], v173 offset:16384
	ds_read_b128 v[216:219], v173 offset:17408
	ds_read_b128 v[220:223], v173 offset:18432
	ds_read_b128 v[224:227], v173 offset:19456
	ds_read_b128 v[228:231], v173 offset:20480
	ds_read_b128 v[240:243], v173 offset:21504
	ds_read_b128 v[244:247], v173 offset:22528
	ds_read_b128 v[248:251], v173 offset:23552
	global_load_lds_dwordx4 v132, s[66:67]
	s_add_i32 m0, s63, 0x2000
	s_add_u32 s70, s66, 0x100000
	s_addc_u32 s71, s67, 0
	s_add_i32 s63, s39, s2
	global_load_lds_dwordx4 v136, s[66:67]
	s_mov_b32 m0, s63
	v_lshl_add_u64 v[252:253], s[68:69], 0, v[134:135]
	global_load_lds_dwordx4 v132, s[70:71]
	s_add_i32 m0, s63, 0x2000
	s_nop 0
	global_load_lds_dwordx4 v136, s[70:71]
	v_lshl_add_u64 v[232:233], s[68:69], 0, v[130:131]
	s_mov_b32 m0, s4
	s_nop 0
	global_load_lds_dwordx4 v130, s[68:69]
	s_mov_b32 m0, s5
	s_nop 0
	global_load_lds_dwordx4 v134, s[68:69]
	s_waitcnt vmcnt(8)
	s_waitcnt lgkmcnt(0)
	s_setprio 1
	s_barrier
	v_mfma_f32_16x16x32_bf16 v[62:65], v[146:149], v[212:215], v[62:65]
	v_mfma_f32_16x16x32_bf16 v[62:65], v[176:179], v[216:219], v[62:65]
	v_mfma_f32_16x16x32_bf16 v[46:49], v[176:179], v[224:227], v[46:49]
	v_mfma_f32_16x16x32_bf16 v[46:49], v[146:149], v[220:223], v[46:49]
	v_mfma_f32_16x16x32_bf16 v[30:33], v[146:149], v[228:231], v[30:33]
	v_mfma_f32_16x16x32_bf16 v[30:33], v[176:179], v[240:243], v[30:33]
	v_mfma_f32_16x16x32_bf16 v[14:17], v[176:179], v[248:251], v[14:17]
	v_mfma_f32_16x16x32_bf16 v[14:17], v[146:149], v[244:247], v[14:17]
	v_mfma_f32_16x16x32_bf16 v[10:13], v[180:183], v[244:247], v[10:13]
	v_mfma_f32_16x16x32_bf16 v[10:13], v[184:187], v[248:251], v[10:13]
	v_mfma_f32_16x16x32_bf16 v[58:61], v[184:187], v[216:219], v[58:61]
	v_mfma_f32_16x16x32_bf16 v[58:61], v[180:183], v[212:215], v[58:61]
	v_mfma_f32_16x16x32_bf16 v[42:45], v[180:183], v[220:223], v[42:45]
	v_mfma_f32_16x16x32_bf16 v[42:45], v[184:187], v[224:227], v[42:45]
	v_mfma_f32_16x16x32_bf16 v[26:29], v[184:187], v[240:243], v[26:29]
	v_mfma_f32_16x16x32_bf16 v[26:29], v[180:183], v[228:231], v[26:29]
	s_setprio 0
	s_setprio 1
	v_mfma_f32_16x16x32_bf16 v[22:25], v[188:191], v[228:231], v[22:25]
	v_mfma_f32_16x16x32_bf16 v[22:25], v[200:203], v[240:243], v[22:25]
	v_mfma_f32_16x16x32_bf16 v[54:57], v[200:203], v[216:219], v[54:57]
	v_mfma_f32_16x16x32_bf16 v[54:57], v[188:191], v[212:215], v[54:57]
	v_mfma_f32_16x16x32_bf16 v[38:41], v[188:191], v[220:223], v[38:41]
	v_mfma_f32_16x16x32_bf16 v[38:41], v[200:203], v[224:227], v[38:41]
	v_mfma_f32_16x16x32_bf16 v[6:9], v[200:203], v[248:251], v[6:9]
	v_mfma_f32_16x16x32_bf16 v[6:9], v[188:191], v[244:247], v[6:9]
	v_mfma_f32_16x16x32_bf16 v[2:5], v[204:207], v[244:247], v[2:5]
	v_mfma_f32_16x16x32_bf16 v[2:5], v[208:211], v[248:251], v[2:5]
	v_mfma_f32_16x16x32_bf16 v[50:53], v[208:211], v[216:219], v[50:53]
	v_mfma_f32_16x16x32_bf16 v[50:53], v[204:207], v[212:215], v[50:53]
	v_mfma_f32_16x16x32_bf16 v[34:37], v[204:207], v[220:223], v[34:37]
	v_mfma_f32_16x16x32_bf16 v[34:37], v[208:211], v[224:227], v[34:37]
	v_mfma_f32_16x16x32_bf16 v[18:21], v[208:211], v[240:243], v[18:21]
	v_mfma_f32_16x16x32_bf16 v[18:21], v[204:207], v[228:231], v[18:21]
	s_barrier
; #define PG8_STAGE(bufoff, gbase, voff) do { _Pragma("unroll") for (int _i = 0; _i < 2; ++_i) \
;         __builtin_amdgcn_global_load_lds((const unsigned*)((const char*)(gbase) + (voff)[_i]), (PG8_LAS unsigned*)(lds + (bufoff) + ldsw + _i * 8192), 16, 0, 0); } while (0)
; #define PG8_LDA(dst, b, h) do { _Pragma("unroll") for (int m = 0; m < 4; ++m) _Pragma("unroll") for (int k = 0; k < 2; ++k) dst[m][k] = *(const PG8_LAS bf16x8*)(lds + PG8_SA(b, h) + aoff + m * 2048 + k * 1024); } while (0)
; #define PG8_LDB(dst, b, h) do { _Pragma("unroll") for (int n = 0; n < 2; ++n) _Pragma("unroll") for (int k = 0; k < 2; ++k) dst[n][k] = *(const PG8_LAS bf16x8*)(lds + PG8_SB(b, h) + boff + n * 2048 + k * 1024); } while (0)
; #define PG8_MMA(ai, bj, At, Bt) do { __builtin_amdgcn_s_setprio(1); _Pragma("unroll") for (int m = 0; m < 4; ++m) _Pragma("unroll") for (int n = 0; n < 2; ++n) _Pragma("unroll") for (int k = 0; k < 2; ++k) \
;         acc[ai][bj][m][n] = __builtin_amdgcn_mfma_f32_16x16x32_bf16(Bt[n][k], At[m][k], acc[ai][bj][m][n], 0, 0, 0); __builtin_amdgcn_s_setprio(0); } while (0)
; #define PG8_WAIT_V(n) asm volatile("s_waitcnt vmcnt(" #n ")" ::: "memory")
; #define PG8_WAIT_L(n) asm volatile("s_waitcnt lgkmcnt(" #n ")" ::: "memory")
; #define PG8_BAR __builtin_amdgcn_s_barrier()
; #define PG8_SCHED __builtin_amdgcn_sched_barrier(0)
; template <class Epi, class Sched, bool ALIGN_EPI = false, bool SP2 = false>
; __device__ __forceinline__ void gemm_phase(PG8_LAS unsigned char* lds, const Gemm g, const Sched& S, const Epi& E) {
;     ...
;             PG8_LDB(B0, 1, 0); PG8_LDB(B1, 1, 1); PG8_SCHED; PG8_LDA(At, 1, 0); PG8_STAGE(PG8_SA(0, 1), a2 + hstep, voffA);
;             PG8_WAIT_V(8); PG8_WAIT_L(0); PG8_BAR; PG8_MMA(0, 0, At, B0); PG8_MMA(0, 1, At, B1); PG8_BAR; PG8_SCHED;
;             PG8_LDA(At, 1, 1); PG8_STAGE(PG8_SB(1, 0), b3, voffB); PG8_STAGE(PG8_SB(1, 1), b3 + hstep, voffB); PG8_STAGE(PG8_SA(1, 0), a3, voffA);
;             PG8_WAIT_V(8); PG8_WAIT_L(0); PG8_BAR; PG8_MMA(1, 0, At, B0); PG8_MMA(1, 1, At, B1); PG8_BAR; PG8_SCHED;
	s_setprio 0
	s_add_i32 s63, 0, 0x18000
	v_add_u32_e32 v175, s63, v153
	s_add_i32 s70, 0, 0x1c000
	ds_read_b128 v[146:149], v175
	ds_read_b128 v[176:179], v175 offset:1024
	ds_read_b128 v[180:183], v175 offset:2048
	ds_read_b128 v[184:187], v175 offset:3072
	v_add_u32_e32 v175, s70, v153
	ds_read_b128 v[188:191], v175
	ds_read_b128 v[200:203], v175 offset:1024
	ds_read_b128 v[204:207], v175 offset:2048
	ds_read_b128 v[208:211], v175 offset:3072
	s_add_u32 s68, s68, 0x100000
	s_addc_u32 s69, s69, 0
	s_mov_b32 m0, s16
	ds_read_b128 v[212:215], v173 offset:32768
	ds_read_b128 v[216:219], v173 offset:33792
	ds_read_b128 v[220:223], v173 offset:34816
	ds_read_b128 v[224:227], v173 offset:35840
	ds_read_b128 v[228:231], v173 offset:36864
	ds_read_b128 v[240:243], v173 offset:37888
	ds_read_b128 v[244:247], v173 offset:38912
	ds_read_b128 v[248:251], v173 offset:39936
	global_load_lds_dwordx4 v130, s[68:69]
	s_mov_b32 m0, s17
	s_nop 0
	global_load_lds_dwordx4 v134, s[68:69]
	s_waitcnt vmcnt(8)
	s_waitcnt lgkmcnt(0)
	s_setprio 1
	s_barrier
	v_mfma_f32_16x16x32_bf16 v[126:129], v[146:149], v[212:215], v[126:129]
	v_mfma_f32_16x16x32_bf16 v[126:129], v[176:179], v[216:219], v[126:129]
	v_mfma_f32_16x16x32_bf16 v[110:113], v[176:179], v[224:227], v[110:113]
	v_mfma_f32_16x16x32_bf16 v[110:113], v[146:149], v[220:223], v[110:113]
	v_mfma_f32_16x16x32_bf16 v[94:97], v[146:149], v[228:231], v[94:97]
	v_mfma_f32_16x16x32_bf16 v[94:97], v[176:179], v[240:243], v[94:97]
	v_mfma_f32_16x16x32_bf16 v[78:81], v[176:179], v[248:251], v[78:81]
	v_mfma_f32_16x16x32_bf16 v[78:81], v[146:149], v[244:247], v[78:81]
	v_mfma_f32_16x16x32_bf16 v[74:77], v[180:183], v[244:247], v[74:77]
	v_mfma_f32_16x16x32_bf16 v[74:77], v[184:187], v[248:251], v[74:77]
	v_mfma_f32_16x16x32_bf16 v[122:125], v[184:187], v[216:219], v[122:125]
	v_mfma_f32_16x16x32_bf16 v[122:125], v[180:183], v[212:215], v[122:125]
	v_mfma_f32_16x16x32_bf16 v[106:109], v[180:183], v[220:223], v[106:109]
	v_mfma_f32_16x16x32_bf16 v[106:109], v[184:187], v[224:227], v[106:109]
	v_mfma_f32_16x16x32_bf16 v[90:93], v[184:187], v[240:243], v[90:93]
	v_mfma_f32_16x16x32_bf16 v[90:93], v[180:183], v[228:231], v[90:93]
	s_setprio 0
	s_setprio 1
	v_mfma_f32_16x16x32_bf16 v[86:89], v[188:191], v[228:231], v[86:89]
	v_mfma_f32_16x16x32_bf16 v[86:89], v[200:203], v[240:243], v[86:89]
	v_mfma_f32_16x16x32_bf16 v[118:121], v[200:203], v[216:219], v[118:121]
	v_mfma_f32_16x16x32_bf16 v[118:121], v[188:191], v[212:215], v[118:121]
	v_mfma_f32_16x16x32_bf16 v[102:105], v[188:191], v[220:223], v[102:105]
	v_mfma_f32_16x16x32_bf16 v[102:105], v[200:203], v[224:227], v[102:105]
	v_mfma_f32_16x16x32_bf16 v[70:73], v[200:203], v[248:251], v[70:73]
	v_mfma_f32_16x16x32_bf16 v[70:73], v[188:191], v[244:247], v[70:73]
	v_mfma_f32_16x16x32_bf16 v[66:69], v[204:207], v[244:247], v[66:69]
	v_mfma_f32_16x16x32_bf16 v[66:69], v[208:211], v[248:251], v[66:69]
	v_mfma_f32_16x16x32_bf16 v[114:117], v[208:211], v[216:219], v[114:117]
	v_mfma_f32_16x16x32_bf16 v[114:117], v[204:207], v[212:215], v[114:117]
	v_mfma_f32_16x16x32_bf16 v[98:101], v[204:207], v[220:223], v[98:101]
	v_mfma_f32_16x16x32_bf16 v[98:101], v[208:211], v[224:227], v[98:101]
	v_mfma_f32_16x16x32_bf16 v[82:85], v[208:211], v[240:243], v[82:85]
	v_mfma_f32_16x16x32_bf16 v[82:85], v[204:207], v[228:231], v[82:85]
	s_barrier
	s_setprio 0
	s_add_i32 s63, s63, s2
	s_add_u32 s98, s66, s44
	s_addc_u32 s99, s67, s45
	s_mov_b32 m0, s63
	ds_read_b128 v[212:215], v173 offset:49152
	ds_read_b128 v[216:219], v173 offset:50176
	ds_read_b128 v[220:223], v173 offset:51200
	ds_read_b128 v[224:227], v173 offset:52224
	ds_read_b128 v[228:231], v173 offset:53248
	ds_read_b128 v[240:243], v173 offset:54272
	ds_read_b128 v[244:247], v173 offset:55296
	ds_read_b128 v[248:251], v173 offset:56320
	global_load_lds_dwordx4 v132, s[98:99]
	s_add_i32 m0, s63, 0x2000
	s_add_u32 s66, s66, 0x100080
	s_addc_u32 s67, s67, 0
	s_add_i32 s63, s70, s2
	global_load_lds_dwordx4 v136, s[98:99]
	s_mov_b32 m0, s63
	s_nop 0
	global_load_lds_dwordx4 v132, s[66:67]
	s_add_i32 m0, s63, 0x2000
	s_nop 0
	global_load_lds_dwordx4 v136, s[66:67]
	v_lshl_add_u64 v[150:151], v[232:233], 0, s[44:45]
	s_mov_b32 m0, s26
	s_nop 0
	global_load_lds_dwordx4 v[150:151], off
	v_lshl_add_u64 v[150:151], v[252:253], 0, s[44:45]
	s_mov_b32 m0, s27
	s_nop 0
	global_load_lds_dwordx4 v[150:151], off
	s_waitcnt vmcnt(8)
	s_waitcnt lgkmcnt(0)
	s_setprio 1
	s_barrier
	v_mfma_f32_16x16x32_bf16 v[62:65], v[146:149], v[212:215], v[62:65]
	v_mfma_f32_16x16x32_bf16 v[62:65], v[176:179], v[216:219], v[62:65]
	v_mfma_f32_16x16x32_bf16 v[46:49], v[176:179], v[224:227], v[46:49]
	v_mfma_f32_16x16x32_bf16 v[46:49], v[146:149], v[220:223], v[46:49]
	v_mfma_f32_16x16x32_bf16 v[30:33], v[146:149], v[228:231], v[30:33]
	v_mfma_f32_16x16x32_bf16 v[30:33], v[176:179], v[240:243], v[30:33]
	v_mfma_f32_16x16x32_bf16 v[14:17], v[176:179], v[248:251], v[14:17]
	v_mfma_f32_16x16x32_bf16 v[14:17], v[146:149], v[244:247], v[14:17]
	v_mfma_f32_16x16x32_bf16 v[10:13], v[180:183], v[244:247], v[10:13]
	v_mfma_f32_16x16x32_bf16 v[10:13], v[184:187], v[248:251], v[10:13]
	v_mfma_f32_16x16x32_bf16 v[58:61], v[184:187], v[216:219], v[58:61]
	v_mfma_f32_16x16x32_bf16 v[58:61], v[180:183], v[212:215], v[58:61]
	v_mfma_f32_16x16x32_bf16 v[42:45], v[180:183], v[220:223], v[42:45]
	v_mfma_f32_16x16x32_bf16 v[42:45], v[184:187], v[224:227], v[42:45]
	v_mfma_f32_16x16x32_bf16 v[26:29], v[184:187], v[240:243], v[26:29]
	v_mfma_f32_16x16x32_bf16 v[26:29], v[180:183], v[228:231], v[26:29]
	s_setprio 0
	s_setprio 1
	v_mfma_f32_16x16x32_bf16 v[22:25], v[188:191], v[228:231], v[22:25]
	v_mfma_f32_16x16x32_bf16 v[22:25], v[200:203], v[240:243], v[22:25]
	v_mfma_f32_16x16x32_bf16 v[54:57], v[200:203], v[216:219], v[54:57]
	v_mfma_f32_16x16x32_bf16 v[54:57], v[188:191], v[212:215], v[54:57]
	v_mfma_f32_16x16x32_bf16 v[38:41], v[188:191], v[220:223], v[38:41]
	v_mfma_f32_16x16x32_bf16 v[38:41], v[200:203], v[224:227], v[38:41]
	v_mfma_f32_16x16x32_bf16 v[6:9], v[200:203], v[248:251], v[6:9]
	v_mfma_f32_16x16x32_bf16 v[6:9], v[188:191], v[244:247], v[6:9]
	v_mfma_f32_16x16x32_bf16 v[2:5], v[204:207], v[244:247], v[2:5]
	v_mfma_f32_16x16x32_bf16 v[2:5], v[208:211], v[248:251], v[2:5]
	v_mfma_f32_16x16x32_bf16 v[50:53], v[208:211], v[216:219], v[50:53]
	v_mfma_f32_16x16x32_bf16 v[50:53], v[204:207], v[212:215], v[50:53]
	v_mfma_f32_16x16x32_bf16 v[34:37], v[204:207], v[220:223], v[34:37]
	v_mfma_f32_16x16x32_bf16 v[34:37], v[208:211], v[224:227], v[34:37]
	v_mfma_f32_16x16x32_bf16 v[18:21], v[208:211], v[240:243], v[18:21]
	v_mfma_f32_16x16x32_bf16 v[18:21], v[204:207], v[228:231], v[18:21]
	s_barrier
	s_setprio 0
	s_add_i32 s61, s61, 2
	s_add_u32 s64, s64, 0x100
	s_addc_u32 s65, s65, 0
	s_add_u32 s53, s53, 0x100
	s_addc_u32 s55, s55, 0
	s_cmp_gt_u32 s61, 61
	s_cbranch_scc0 .LBB0_1203
	s_and_b64 vcc, exec, s[46:47]
	s_cbranch_vccz .LBB0_1206
	s_barrier

; #define PG8_STAGE(bufoff, gbase, voff) do { _Pragma("unroll") for (int _i = 0; _i < 2; ++_i) \
;         __builtin_amdgcn_global_load_lds((const unsigned*)((const char*)(gbase) + (voff)[_i]), (PG8_LAS unsigned*)(lds + (bufoff) + ldsw + _i * 8192), 16, 0, 0); } while (0)
; #define PG8_LDA(dst, b, h) do { _Pragma("unroll") for (int m = 0; m < 4; ++m) _Pragma("unroll") for (int k = 0; k < 2; ++k) dst[m][k] = *(const PG8_LAS bf16x8*)(lds + PG8_SA(b, h) + aoff + m * 2048 + k * 1024); } while (0)
; #define PG8_LDB(dst, b, h) do { _Pragma("unroll") for (int n = 0; n < 2; ++n) _Pragma("unroll") for (int k = 0; k < 2; ++k) dst[n][k] = *(const PG8_LAS bf16x8*)(lds + PG8_SB(b, h) + boff + n * 2048 + k * 1024); } while (0)
; #define PG8_MMA(ai, bj, At, Bt) do { __builtin_amdgcn_s_setprio(1); _Pragma("unroll") for (int m = 0; m < 4; ++m) _Pragma("unroll") for (int n = 0; n < 2; ++n) _Pragma("unroll") for (int k = 0; k < 2; ++k) \
;         acc[ai][bj][m][n] = __builtin_amdgcn_mfma_f32_16x16x32_bf16(Bt[n][k], At[m][k], acc[ai][bj][m][n], 0, 0, 0); __builtin_amdgcn_s_setprio(0); } while (0)
; #define PG8_WAIT_V(n) asm volatile("s_waitcnt vmcnt(" #n ")" ::: "memory")
; #define PG8_WAIT_L(n) asm volatile("s_waitcnt lgkmcnt(" #n ")" ::: "memory")
; template <class Epi, class Sched, bool ALIGN_EPI = false, bool SP2 = false>
; __device__ __forceinline__ void gemm_phase(PG8_LAS unsigned char* lds, const Gemm g, const Sched& S, const Epi& E) {
;     ...
;             const bool last = (t == nt - 2);
;             const char* a1 = cA + (size_t)(t + 1) * kstep;
;             const char* a2 = last ? nA : cA + (size_t)(t + 2) * kstep; const char* b2 = last ? nB : cB + (size_t)(t + 2) * kstep;
;             const char* a3 = a2 + kstep; const char* b3 = b2 + kstep;
;             if (last && has_next) S.a_ready(nxt);
;             if constexpr (SP2) {
;             PG8_LDB(B0, 0, 0); PG8_LDB(B1, 0, 1); PG8_SCHED; PG8_LDA(At, 0, 0); PG8_STAGE(PG8_SA(1, 1), a1 + hstep, voffA);
;             PG8_WAIT_V(8); PG8_WAIT_L(0); PG8_BAR; PG8_MMA(0, 0, At, B0); PG8_MMA(0, 1, At, B1); PG8_BAR; PG8_SCHED;
;             PG8_LDA(At, 0, 1); PG8_STAGE(PG8_SB(0, 0), b2, voffB); PG8_STAGE(PG8_SB(0, 1), b2 + hstep, voffB); PG8_STAGE(PG8_SA(0, 0), a2, voffA);
;             PG8_WAIT_V(8); PG8_WAIT_L(0); PG8_BAR; PG8_MMA(1, 0, At, B0); PG8_MMA(1, 1, At, B1); PG8_BAR; PG8_SCHED;
.LBB0_1746:
	ds_read_b128 v[140:143], v134
	ds_read_b128 v[144:147], v134 offset:1024
	ds_read_b128 v[148:151], v134 offset:2048
	ds_read_b128 v[152:155], v134 offset:3072
	ds_read_b128 v[156:159], v135
	ds_read_b128 v[160:163], v135 offset:1024
	ds_read_b128 v[164:167], v135 offset:2048
	ds_read_b128 v[168:171], v135 offset:3072
	s_add_i32 s36, s38, 2
	s_mov_b32 s37, s11
	s_or_b32 s10, s38, 1
	s_lshl_b64 s[40:41], s[36:37], 7
	s_cmp_lg_u32 s38, s42
	s_cselect_b32 s38, s40, 0
	s_cselect_b32 s37, s41, 0
	s_add_u32 s40, s6, s38
	s_addc_u32 s41, s7, s37
	s_add_u32 s38, s2, s38
	s_addc_u32 s39, s3, s37
	s_lshl_b64 s[52:53], s[10:11], 7
	s_add_u32 s52, s8, s52
	s_addc_u32 s53, s9, s53
	s_mov_b32 m0, s43
	ds_read_b128 v[172:175], v136
	ds_read_b128 v[176:179], v136 offset:1024
	ds_read_b128 v[180:183], v136 offset:2048
	ds_read_b128 v[184:187], v136 offset:3072
	ds_read_b128 v[188:191], v136 offset:4096
	ds_read_b128 v[196:199], v136 offset:5120
	ds_read_b128 v[202:205], v136 offset:6144
	ds_read_b128 v[206:209], v136 offset:7168
	global_load_lds_dwordx4 v128, s[52:53]
	s_mov_b32 m0, s44
	s_nop 0
	global_load_lds_dwordx4 v130, s[52:53]
	s_waitcnt vmcnt(8)
	s_waitcnt lgkmcnt(0)
	s_setprio 1
	s_barrier
	v_mfma_f32_16x16x32_bf16 v[124:127], v[140:143], v[172:175], v[124:127]
	v_mfma_f32_16x16x32_bf16 v[124:127], v[144:147], v[176:179], v[124:127]
	v_mfma_f32_16x16x32_bf16 v[116:119], v[144:147], v[184:187], v[116:119]
	v_mfma_f32_16x16x32_bf16 v[116:119], v[140:143], v[180:183], v[116:119]
	v_mfma_f32_16x16x32_bf16 v[104:107], v[140:143], v[188:191], v[104:107]
	v_mfma_f32_16x16x32_bf16 v[104:107], v[144:147], v[196:199], v[104:107]
	v_mfma_f32_16x16x32_bf16 v[88:91], v[144:147], v[206:209], v[88:91]
	v_mfma_f32_16x16x32_bf16 v[88:91], v[140:143], v[202:205], v[88:91]
	v_mfma_f32_16x16x32_bf16 v[80:83], v[148:151], v[202:205], v[80:83]
	v_mfma_f32_16x16x32_bf16 v[80:83], v[152:155], v[206:209], v[80:83]
	v_mfma_f32_16x16x32_bf16 v[120:123], v[152:155], v[176:179], v[120:123]
	v_mfma_f32_16x16x32_bf16 v[120:123], v[148:151], v[172:175], v[120:123]
	v_mfma_f32_16x16x32_bf16 v[112:115], v[148:151], v[180:183], v[112:115]
	v_mfma_f32_16x16x32_bf16 v[112:115], v[152:155], v[184:187], v[112:115]
	v_mfma_f32_16x16x32_bf16 v[96:99], v[152:155], v[196:199], v[96:99]
	v_mfma_f32_16x16x32_bf16 v[96:99], v[148:151], v[188:191], v[96:99]
	s_setprio 0
	s_setprio 1
	v_mfma_f32_16x16x32_bf16 v[76:79], v[156:159], v[188:191], v[76:79]
	v_mfma_f32_16x16x32_bf16 v[76:79], v[160:163], v[196:199], v[76:79]
	v_mfma_f32_16x16x32_bf16 v[108:111], v[160:163], v[176:179], v[108:111]
	v_mfma_f32_16x16x32_bf16 v[108:111], v[156:159], v[172:175], v[108:111]
	v_mfma_f32_16x16x32_bf16 v[92:95], v[156:159], v[180:183], v[92:95]
	v_mfma_f32_16x16x32_bf16 v[92:95], v[160:163], v[184:187], v[92:95]
	v_mfma_f32_16x16x32_bf16 v[68:71], v[160:163], v[206:209], v[68:71]
	v_mfma_f32_16x16x32_bf16 v[68:71], v[156:159], v[202:205], v[68:71]
	v_mfma_f32_16x16x32_bf16 v[64:67], v[164:167], v[202:205], v[64:67]
	v_mfma_f32_16x16x32_bf16 v[64:67], v[168:171], v[206:209], v[64:67]
	v_mfma_f32_16x16x32_bf16 v[100:103], v[168:171], v[176:179], v[100:103]
	v_mfma_f32_16x16x32_bf16 v[100:103], v[164:167], v[172:175], v[100:103]
	v_mfma_f32_16x16x32_bf16 v[84:87], v[164:167], v[180:183], v[84:87]
	v_mfma_f32_16x16x32_bf16 v[84:87], v[168:171], v[184:187], v[84:87]
	v_mfma_f32_16x16x32_bf16 v[72:75], v[168:171], v[196:199], v[72:75]
	v_mfma_f32_16x16x32_bf16 v[72:75], v[164:167], v[188:191], v[72:75]
	s_barrier
	s_setprio 0
	s_mov_b32 m0, s31
	s_add_u32 s52, s38, 0x2b0000
	ds_read_b128 v[172:175], v136 offset:16384
	ds_read_b128 v[176:179], v136 offset:17408
	ds_read_b128 v[180:183], v136 offset:18432
	ds_read_b128 v[184:187], v136 offset:19456
	ds_read_b128 v[188:191], v136 offset:20480
	ds_read_b128 v[196:199], v136 offset:21504
	ds_read_b128 v[202:205], v136 offset:22528
	ds_read_b128 v[206:209], v136 offset:23552
	global_load_lds_dwordx4 v128, s[38:39]
	s_mov_b32 m0, s45
	s_addc_u32 s53, s39, 0
	global_load_lds_dwordx4 v130, s[38:39]
	s_mov_b32 m0, s46
	v_lshl_add_u64 v[212:213], s[40:41], 0, v[130:131]
	global_load_lds_dwordx4 v128, s[52:53]
	s_mov_b32 m0, s47
	s_nop 0
	global_load_lds_dwordx4 v130, s[52:53]
	v_lshl_add_u64 v[210:211], s[40:41], 0, v[128:129]
	s_mov_b32 m0, s26
	s_nop 0
	global_load_lds_dwordx4 v128, s[40:41]
	s_mov_b32 m0, s27
	s_nop 0
	global_load_lds_dwordx4 v130, s[40:41]
	s_waitcnt vmcnt(8)
	s_waitcnt lgkmcnt(0)
	s_setprio 1
	s_barrier
	v_mfma_f32_16x16x32_bf16 v[60:63], v[140:143], v[172:175], v[60:63]
	v_mfma_f32_16x16x32_bf16 v[60:63], v[144:147], v[176:179], v[60:63]
	v_mfma_f32_16x16x32_bf16 v[52:55], v[144:147], v[184:187], v[52:55]
	v_mfma_f32_16x16x32_bf16 v[52:55], v[140:143], v[180:183], v[52:55]
	v_mfma_f32_16x16x32_bf16 v[40:43], v[140:143], v[188:191], v[40:43]
	v_mfma_f32_16x16x32_bf16 v[40:43], v[144:147], v[196:199], v[40:43]
	v_mfma_f32_16x16x32_bf16 v[24:27], v[144:147], v[206:209], v[24:27]
	v_mfma_f32_16x16x32_bf16 v[24:27], v[140:143], v[202:205], v[24:27]
	v_mfma_f32_16x16x32_bf16 v[16:19], v[148:151], v[202:205], v[16:19]
	v_mfma_f32_16x16x32_bf16 v[16:19], v[152:155], v[206:209], v[16:19]
	v_mfma_f32_16x16x32_bf16 v[56:59], v[152:155], v[176:179], v[56:59]
	v_mfma_f32_16x16x32_bf16 v[56:59], v[148:151], v[172:175], v[56:59]
	v_mfma_f32_16x16x32_bf16 v[48:51], v[148:151], v[180:183], v[48:51]
	v_mfma_f32_16x16x32_bf16 v[48:51], v[152:155], v[184:187], v[48:51]
	v_mfma_f32_16x16x32_bf16 v[32:35], v[152:155], v[196:199], v[32:35]
	v_mfma_f32_16x16x32_bf16 v[32:35], v[148:151], v[188:191], v[32:35]
	s_setprio 0
	s_setprio 1
	v_mfma_f32_16x16x32_bf16 v[12:15], v[156:159], v[188:191], v[12:15]
	v_mfma_f32_16x16x32_bf16 v[12:15], v[160:163], v[196:199], v[12:15]
	v_mfma_f32_16x16x32_bf16 v[44:47], v[160:163], v[176:179], v[44:47]
	v_mfma_f32_16x16x32_bf16 v[44:47], v[156:159], v[172:175], v[44:47]
	v_mfma_f32_16x16x32_bf16 v[28:31], v[156:159], v[180:183], v[28:31]
	v_mfma_f32_16x16x32_bf16 v[28:31], v[160:163], v[184:187], v[28:31]
	v_mfma_f32_16x16x32_bf16 v[4:7], v[160:163], v[206:209], v[4:7]
	v_mfma_f32_16x16x32_bf16 v[4:7], v[156:159], v[202:205], v[4:7]
	v_mfma_f32_16x16x32_bf16 v[0:3], v[164:167], v[202:205], v[0:3]
	v_mfma_f32_16x16x32_bf16 v[0:3], v[168:171], v[206:209], v[0:3]
	v_mfma_f32_16x16x32_bf16 v[36:39], v[168:171], v[176:179], v[36:39]
	v_mfma_f32_16x16x32_bf16 v[36:39], v[164:167], v[172:175], v[36:39]
	v_mfma_f32_16x16x32_bf16 v[20:23], v[164:167], v[180:183], v[20:23]
	v_mfma_f32_16x16x32_bf16 v[20:23], v[168:171], v[184:187], v[20:23]
	v_mfma_f32_16x16x32_bf16 v[8:11], v[168:171], v[196:199], v[8:11]
	v_mfma_f32_16x16x32_bf16 v[8:11], v[164:167], v[188:191], v[8:11]
	s_barrier
; #define PG8_STAGE(bufoff, gbase, voff) do { _Pragma("unroll") for (int _i = 0; _i < 2; ++_i) \
;         __builtin_amdgcn_global_load_lds((const unsigned*)((const char*)(gbase) + (voff)[_i]), (PG8_LAS unsigned*)(lds + (bufoff) + ldsw + _i * 8192), 16, 0, 0); } while (0)
; #define PG8_LDA(dst, b, h) do { _Pragma("unroll") for (int m = 0; m < 4; ++m) _Pragma("unroll") for (int k = 0; k < 2; ++k) dst[m][k] = *(const PG8_LAS bf16x8*)(lds + PG8_SA(b, h) + aoff + m * 2048 + k * 1024); } while (0)
; #define PG8_LDB(dst, b, h) do { _Pragma("unroll") for (int n = 0; n < 2; ++n) _Pragma("unroll") for (int k = 0; k < 2; ++k) dst[n][k] = *(const PG8_LAS bf16x8*)(lds + PG8_SB(b, h) + boff + n * 2048 + k * 1024); } while (0)
; #define PG8_MMA(ai, bj, At, Bt) do { __builtin_amdgcn_s_setprio(1); _Pragma("unroll") for (int m = 0; m < 4; ++m) _Pragma("unroll") for (int n = 0; n < 2; ++n) _Pragma("unroll") for (int k = 0; k < 2; ++k) \
;         acc[ai][bj][m][n] = __builtin_amdgcn_mfma_f32_16x16x32_bf16(Bt[n][k], At[m][k], acc[ai][bj][m][n], 0, 0, 0); __builtin_amdgcn_s_setprio(0); } while (0)
; #define PG8_WAIT_V(n) asm volatile("s_waitcnt vmcnt(" #n ")" ::: "memory")
; #define PG8_WAIT_L(n) asm volatile("s_waitcnt lgkmcnt(" #n ")" ::: "memory")
; #define PG8_BAR __builtin_amdgcn_s_barrier()
; #define PG8_SCHED __builtin_amdgcn_sched_barrier(0)
; template <class Epi, class Sched, bool ALIGN_EPI = false, bool SP2 = false>
; __device__ __forceinline__ void gemm_phase(PG8_LAS unsigned char* lds, const Gemm g, const Sched& S, const Epi& E) {
;     ...
;             PG8_LDB(B0, 1, 0); PG8_LDB(B1, 1, 1); PG8_SCHED; PG8_LDA(At, 1, 0); PG8_STAGE(PG8_SA(0, 1), a2 + hstep, voffA);
;             PG8_WAIT_V(8); PG8_WAIT_L(0); PG8_BAR; PG8_MMA(0, 0, At, B0); PG8_MMA(0, 1, At, B1); PG8_BAR; PG8_SCHED;
;             PG8_LDA(At, 1, 1); PG8_STAGE(PG8_SB(1, 0), b3, voffB); PG8_STAGE(PG8_SB(1, 1), b3 + hstep, voffB); PG8_STAGE(PG8_SA(1, 0), a3, voffA);
;             PG8_WAIT_V(8); PG8_WAIT_L(0); PG8_BAR; PG8_MMA(1, 0, At, B0); PG8_MMA(1, 1, At, B1); PG8_BAR; PG8_SCHED;
;     ...
;         if constexpr (ALIGN_EPI) { if (wr == 0) PG8_BAR; }
;         if constexpr (!Epi::AFTER_DRAIN) { E(acc, cur, wr, wc, fr, fq); S.done(cur); }
;         if (!has_next) break;
	s_setprio 0
	ds_read_b128 v[140:143], v137
	ds_read_b128 v[144:147], v137 offset:1024
	ds_read_b128 v[148:151], v137 offset:2048
	ds_read_b128 v[152:155], v137 offset:3072
	ds_read_b128 v[156:159], v138
	ds_read_b128 v[160:163], v138 offset:1024
	ds_read_b128 v[164:167], v138 offset:2048
	ds_read_b128 v[168:171], v138 offset:3072
	s_add_u32 s40, s40, 0x2b0000
	s_addc_u32 s41, s41, 0
	s_mov_b32 m0, s28
	ds_read_b128 v[172:175], v136 offset:32768
	ds_read_b128 v[176:179], v136 offset:33792
	ds_read_b128 v[180:183], v136 offset:34816
	ds_read_b128 v[184:187], v136 offset:35840
	ds_read_b128 v[188:191], v136 offset:36864
	ds_read_b128 v[196:199], v136 offset:37888
	ds_read_b128 v[202:205], v136 offset:38912
	ds_read_b128 v[206:209], v136 offset:39936
	global_load_lds_dwordx4 v128, s[40:41]
	s_mov_b32 m0, s30
	s_nop 0
	global_load_lds_dwordx4 v130, s[40:41]
	s_waitcnt vmcnt(8)
	s_waitcnt lgkmcnt(0)
	s_setprio 1
	s_barrier
	v_mfma_f32_16x16x32_bf16 v[124:127], v[140:143], v[172:175], v[124:127]
	v_mfma_f32_16x16x32_bf16 v[124:127], v[144:147], v[176:179], v[124:127]
	v_mfma_f32_16x16x32_bf16 v[116:119], v[144:147], v[184:187], v[116:119]
	v_mfma_f32_16x16x32_bf16 v[116:119], v[140:143], v[180:183], v[116:119]
	v_mfma_f32_16x16x32_bf16 v[104:107], v[140:143], v[188:191], v[104:107]
	v_mfma_f32_16x16x32_bf16 v[104:107], v[144:147], v[196:199], v[104:107]
	v_mfma_f32_16x16x32_bf16 v[88:91], v[144:147], v[206:209], v[88:91]
	v_mfma_f32_16x16x32_bf16 v[88:91], v[140:143], v[202:205], v[88:91]
	v_mfma_f32_16x16x32_bf16 v[80:83], v[148:151], v[202:205], v[80:83]
	v_mfma_f32_16x16x32_bf16 v[80:83], v[152:155], v[206:209], v[80:83]
	v_mfma_f32_16x16x32_bf16 v[120:123], v[152:155], v[176:179], v[120:123]
	v_mfma_f32_16x16x32_bf16 v[120:123], v[148:151], v[172:175], v[120:123]
	v_mfma_f32_16x16x32_bf16 v[112:115], v[148:151], v[180:183], v[112:115]
	v_mfma_f32_16x16x32_bf16 v[112:115], v[152:155], v[184:187], v[112:115]
	v_mfma_f32_16x16x32_bf16 v[96:99], v[152:155], v[196:199], v[96:99]
	v_mfma_f32_16x16x32_bf16 v[96:99], v[148:151], v[188:191], v[96:99]
	s_setprio 0
	s_setprio 1
	v_mfma_f32_16x16x32_bf16 v[76:79], v[156:159], v[188:191], v[76:79]
	v_mfma_f32_16x16x32_bf16 v[76:79], v[160:163], v[196:199], v[76:79]
	v_mfma_f32_16x16x32_bf16 v[108:111], v[160:163], v[176:179], v[108:111]
	v_mfma_f32_16x16x32_bf16 v[108:111], v[156:159], v[172:175], v[108:111]
	v_mfma_f32_16x16x32_bf16 v[92:95], v[156:159], v[180:183], v[92:95]
	v_mfma_f32_16x16x32_bf16 v[92:95], v[160:163], v[184:187], v[92:95]
	v_mfma_f32_16x16x32_bf16 v[68:71], v[160:163], v[206:209], v[68:71]
	v_mfma_f32_16x16x32_bf16 v[68:71], v[156:159], v[202:205], v[68:71]
	v_mfma_f32_16x16x32_bf16 v[64:67], v[164:167], v[202:205], v[64:67]
	v_mfma_f32_16x16x32_bf16 v[64:67], v[168:171], v[206:209], v[64:67]
	v_mfma_f32_16x16x32_bf16 v[100:103], v[168:171], v[176:179], v[100:103]
	v_mfma_f32_16x16x32_bf16 v[100:103], v[164:167], v[172:175], v[100:103]
	v_mfma_f32_16x16x32_bf16 v[84:87], v[164:167], v[180:183], v[84:87]
	v_mfma_f32_16x16x32_bf16 v[84:87], v[168:171], v[184:187], v[84:87]
	v_mfma_f32_16x16x32_bf16 v[72:75], v[168:171], v[196:199], v[72:75]
	v_mfma_f32_16x16x32_bf16 v[72:75], v[164:167], v[188:191], v[72:75]
	s_barrier
	s_setprio 0
	s_mov_b32 m0, s48
	s_add_u32 s98, s38, s12
	s_addc_u32 s99, s39, s13
	s_add_u32 s38, s38, 0x2b0080
	ds_read_b128 v[172:175], v136 offset:49152
	ds_read_b128 v[176:179], v136 offset:50176
	ds_read_b128 v[180:183], v136 offset:51200
	ds_read_b128 v[184:187], v136 offset:52224
	ds_read_b128 v[188:191], v136 offset:53248
	ds_read_b128 v[196:199], v136 offset:54272
	ds_read_b128 v[202:205], v136 offset:55296
	ds_read_b128 v[206:209], v136 offset:56320
	global_load_lds_dwordx4 v128, s[98:99]
	s_mov_b32 m0, s49
	s_addc_u32 s39, s39, 0
	global_load_lds_dwordx4 v130, s[98:99]
	s_mov_b32 m0, s50
	s_nop 0
	global_load_lds_dwordx4 v128, s[38:39]
	s_mov_b32 m0, s51
	s_nop 0
	global_load_lds_dwordx4 v130, s[38:39]
	v_lshl_add_u64 v[192:193], v[210:211], 0, s[12:13]
	s_mov_b32 m0, s34
	s_nop 0
	global_load_lds_dwordx4 v[192:193], off
	v_lshl_add_u64 v[192:193], v[212:213], 0, s[12:13]
	s_mov_b32 m0, s35
	s_nop 0
	global_load_lds_dwordx4 v[192:193], off
	s_waitcnt vmcnt(8)
	s_waitcnt lgkmcnt(0)
	s_setprio 1
	s_barrier
	v_mfma_f32_16x16x32_bf16 v[60:63], v[140:143], v[172:175], v[60:63]
	v_mfma_f32_16x16x32_bf16 v[60:63], v[144:147], v[176:179], v[60:63]
	v_mfma_f32_16x16x32_bf16 v[52:55], v[144:147], v[184:187], v[52:55]
	v_mfma_f32_16x16x32_bf16 v[52:55], v[140:143], v[180:183], v[52:55]
	v_mfma_f32_16x16x32_bf16 v[40:43], v[140:143], v[188:191], v[40:43]
	v_mfma_f32_16x16x32_bf16 v[40:43], v[144:147], v[196:199], v[40:43]
	v_mfma_f32_16x16x32_bf16 v[24:27], v[144:147], v[206:209], v[24:27]
	v_mfma_f32_16x16x32_bf16 v[24:27], v[140:143], v[202:205], v[24:27]
	v_mfma_f32_16x16x32_bf16 v[16:19], v[148:151], v[202:205], v[16:19]
	v_mfma_f32_16x16x32_bf16 v[16:19], v[152:155], v[206:209], v[16:19]
	v_mfma_f32_16x16x32_bf16 v[56:59], v[152:155], v[176:179], v[56:59]
	v_mfma_f32_16x16x32_bf16 v[56:59], v[148:151], v[172:175], v[56:59]
	v_mfma_f32_16x16x32_bf16 v[48:51], v[148:151], v[180:183], v[48:51]
	v_mfma_f32_16x16x32_bf16 v[48:51], v[152:155], v[184:187], v[48:51]
	v_mfma_f32_16x16x32_bf16 v[32:35], v[152:155], v[196:199], v[32:35]
	v_mfma_f32_16x16x32_bf16 v[32:35], v[148:151], v[188:191], v[32:35]
	s_setprio 0
	s_setprio 1
	v_mfma_f32_16x16x32_bf16 v[12:15], v[156:159], v[188:191], v[12:15]
	v_mfma_f32_16x16x32_bf16 v[12:15], v[160:163], v[196:199], v[12:15]
	v_mfma_f32_16x16x32_bf16 v[44:47], v[160:163], v[176:179], v[44:47]
	v_mfma_f32_16x16x32_bf16 v[44:47], v[156:159], v[172:175], v[44:47]
	v_mfma_f32_16x16x32_bf16 v[28:31], v[156:159], v[180:183], v[28:31]
	v_mfma_f32_16x16x32_bf16 v[28:31], v[160:163], v[184:187], v[28:31]
	v_mfma_f32_16x16x32_bf16 v[4:7], v[160:163], v[206:209], v[4:7]
	v_mfma_f32_16x16x32_bf16 v[4:7], v[156:159], v[202:205], v[4:7]
	v_mfma_f32_16x16x32_bf16 v[0:3], v[164:167], v[202:205], v[0:3]
	v_mfma_f32_16x16x32_bf16 v[0:3], v[168:171], v[206:209], v[0:3]
	v_mfma_f32_16x16x32_bf16 v[36:39], v[168:171], v[176:179], v[36:39]
	v_mfma_f32_16x16x32_bf16 v[36:39], v[164:167], v[172:175], v[36:39]
	v_mfma_f32_16x16x32_bf16 v[20:23], v[164:167], v[180:183], v[20:23]
	v_mfma_f32_16x16x32_bf16 v[20:23], v[168:171], v[184:187], v[20:23]
	v_mfma_f32_16x16x32_bf16 v[8:11], v[168:171], v[196:199], v[8:11]
	v_mfma_f32_16x16x32_bf16 v[8:11], v[164:167], v[188:191], v[8:11]
	s_barrier
	s_setprio 0
	s_cmp_ge_u32 s36, s5
	s_mov_b32 s38, s36
	s_cbranch_scc0 .LBB0_1746
	s_cmpk_lt_u32 s16, 0x100
	s_cbranch_scc0 .LBB0_1749
	s_barrier
